# wave_sum butterflies via DPP/permlane swap in conv LayerNorm and norm_pass (bit-identical sums)
# speedup vs baseline: 1.0145x; 1.0070x over previous
.LBB0_292:
	s_or_b64 exec, exec, s[2:3]
	s_waitcnt vmcnt(16) lgkmcnt(0)
	s_barrier
	s_load_dwordx8 s[40:47], s[54:55], 0x60
	v_readlane_b32 s4, v233, 60
	s_mul_i32 s2, s4, 0x7c00
	s_mul_hi_i32 s3, s4, 0x7c00
	v_mov_b32_e32 v11, v169
	s_waitcnt lgkmcnt(0)
	s_add_u32 s2, s40, s2
	s_addc_u32 s3, s41, s3
	v_lshl_add_u64 v[50:51], s[2:3], 0, v[10:11]
	global_load_dwordx2 v[0:1], v10, s[2:3]
	global_load_dwordx2 v[2:3], v10, s[2:3] offset:1024
	global_load_dwordx2 v[4:5], v10, s[2:3] offset:2048
	global_load_dwordx2 v[6:7], v10, s[2:3] offset:3072
	s_add_u32 s2, s42, s56
	s_addc_u32 s3, s43, s57
	global_load_dwordx2 v[12:13], v10, s[2:3]
	v_add_co_u32_e32 v26, vcc, s18, v50
	s_movk_i32 s2, 0x2000
	s_nop 0
	v_addc_co_u32_e32 v27, vcc, 0, v51, vcc
	v_add_co_u32_e32 v28, vcc, s2, v50
	s_movk_i32 s2, 0x3000
	s_nop 0
	v_addc_co_u32_e32 v29, vcc, 0, v51, vcc
	global_load_dwordx2 v[14:15], v[26:27], off offset:1024
	global_load_dwordx2 v[16:17], v[26:27], off offset:2048
	global_load_dwordx2 v[24:25], v[28:29], off offset:-4096
	global_load_dwordx2 v[18:19], v[28:29], off
	global_load_dwordx2 v[20:21], v[28:29], off offset:1024
	global_load_dwordx2 v[22:23], v[28:29], off offset:2048
	v_add_co_u32_e32 v38, vcc, s2, v50
	s_movk_i32 s2, 0x5000
	s_nop 0
	v_addc_co_u32_e32 v39, vcc, 0, v51, vcc
	v_add_co_u32_e32 v42, vcc, s13, v50
	v_readlane_b32 s5, v233, 61
	s_nop 0
	v_addc_co_u32_e32 v43, vcc, 0, v51, vcc
	global_load_dwordx2 v[36:37], v[26:27], off offset:3072
	s_nop 0
	global_load_dwordx2 v[26:27], v[38:39], off offset:1024
	global_load_dwordx2 v[32:33], v[28:29], off offset:3072
	global_load_dwordx2 v[34:35], v[42:43], off offset:-4096
	s_nop 0
	global_load_dwordx2 v[28:29], v[42:43], off
	global_load_dwordx2 v[30:31], v[42:43], off offset:1024
	v_add_co_u32_e32 v62, vcc, s2, v50
	s_movk_i32 s2, 0x6000
	s_nop 0
	v_addc_co_u32_e32 v63, vcc, 0, v51, vcc
	v_add_co_u32_e32 v48, vcc, s2, v50
	s_movk_i32 s2, 0x7000
	s_nop 0
	v_addc_co_u32_e32 v49, vcc, 0, v51, vcc
	global_load_dwordx2 v[52:53], v[38:39], off offset:2048
	global_load_dwordx2 v[54:55], v[38:39], off offset:3072
	s_nop 0
	global_load_dwordx2 v[38:39], v[62:63], off offset:1024
	global_load_dwordx2 v[40:41], v[62:63], off offset:2048
	global_load_dwordx2 v[56:57], v[42:43], off offset:2048
	global_load_dwordx2 v[58:59], v[42:43], off offset:3072
	global_load_dwordx2 v[60:61], v[48:49], off offset:-4096
	s_nop 0
	global_load_dwordx2 v[42:43], v[48:49], off
	global_load_dwordx2 v[44:45], v[48:49], off offset:1024
	global_load_dwordx2 v[46:47], v[48:49], off offset:2048
	s_nop 0
	global_load_dwordx2 v[48:49], v[48:49], off offset:3072
	v_add_co_u32_e32 v50, vcc, s2, v50
	s_add_u32 s2, s44, s56
	s_nop 0
	v_addc_co_u32_e32 v51, vcc, 0, v51, vcc
	global_load_dwordx2 v[66:67], v[62:63], off offset:3072
	s_nop 0
	global_load_dwordx2 v[62:63], v[50:51], off
	global_load_dwordx2 v[64:65], v[50:51], off offset:1024
	s_nop 0
	global_load_dwordx2 v[50:51], v[50:51], off offset:2048
	ds_read2st64_b32 v[72:73], v160 offset1:2
	ds_read2st64_b32 v[74:75], v160 offset0:4 offset1:6
	ds_read2st64_b32 v[76:77], v160 offset0:8 offset1:10
	ds_read2st64_b32 v[78:79], v160 offset0:12 offset1:14
	ds_read2st64_b32 v[80:81], v160 offset0:16 offset1:18
	ds_read2st64_b32 v[82:83], v160 offset0:20 offset1:22
	ds_read2st64_b32 v[84:85], v160 offset0:24 offset1:26
	ds_read2st64_b32 v[86:87], v160 offset0:28 offset1:30
	ds_read2st64_b32 v[92:93], v160 offset0:32 offset1:34
	ds_read2st64_b32 v[94:95], v160 offset0:36 offset1:38
	ds_read2st64_b32 v[96:97], v160 offset0:40 offset1:42
	ds_read2st64_b32 v[98:99], v160 offset0:44 offset1:46
	ds_read2st64_b32 v[100:101], v160 offset0:48 offset1:50
	ds_read2st64_b32 v[102:103], v160 offset0:52 offset1:54
	ds_read2st64_b32 v[106:107], v160 offset0:56 offset1:58
	ds_read2st64_b32 v[112:113], v160 offset0:60 offset1:62
	ds_read2st64_b32 v[126:127], v160 offset0:64 offset1:66
	ds_read2st64_b32 v[142:143], v160 offset0:68 offset1:70
	ds_read2st64_b32 v[132:133], v160 offset0:72 offset1:74
	ds_read2st64_b32 v[118:119], v160 offset0:76 offset1:78
	ds_read2st64_b32 v[90:91], v160 offset0:80 offset1:82
	ds_read2st64_b32 v[70:71], v160 offset0:84 offset1:86
	ds_read2st64_b32 v[68:69], v160 offset0:88 offset1:90
	s_waitcnt lgkmcnt(14)
	v_lshlrev_b32_e32 v88, 16, v72
	v_and_b32_e32 v89, 0xffff0000, v72
	v_lshlrev_b32_e32 v116, 16, v73
	v_and_b32_e32 v117, 0xffff0000, v73
	v_lshlrev_b32_e32 v120, 16, v74
	v_and_b32_e32 v121, 0xffff0000, v74
	v_lshlrev_b32_e32 v130, 16, v75
	v_and_b32_e32 v131, 0xffff0000, v75
	v_lshlrev_b32_e32 v136, 16, v76
	v_and_b32_e32 v137, 0xffff0000, v76
	v_lshlrev_b32_e32 v144, 16, v77
	v_and_b32_e32 v145, 0xffff0000, v77
	v_lshlrev_b32_e32 v148, 16, v78
	v_and_b32_e32 v149, 0xffff0000, v78
	v_lshlrev_b32_e32 v146, 16, v79
	v_and_b32_e32 v147, 0xffff0000, v79
	v_lshlrev_b32_e32 v140, 16, v80
	v_and_b32_e32 v141, 0xffff0000, v80
	v_lshlrev_b32_e32 v134, 16, v81
	v_and_b32_e32 v135, 0xffff0000, v81
	v_lshlrev_b32_e32 v128, 16, v82
	v_and_b32_e32 v129, 0xffff0000, v82
	v_lshlrev_b32_e32 v122, 16, v83
	v_and_b32_e32 v123, 0xffff0000, v83
	v_lshlrev_b32_e32 v114, 16, v84
	v_and_b32_e32 v115, 0xffff0000, v84
	v_lshlrev_b32_e32 v110, 16, v85
	v_and_b32_e32 v111, 0xffff0000, v85
	s_waitcnt lgkmcnt(8)
	v_lshlrev_b32_e32 v104, 16, v106
	v_and_b32_e32 v105, 0xffff0000, v106
	v_lshlrev_b32_e32 v106, 16, v107
	v_and_b32_e32 v107, 0xffff0000, v107
	s_waitcnt lgkmcnt(7)
	v_lshlrev_b32_e32 v108, 16, v112
	v_and_b32_e32 v109, 0xffff0000, v112
	s_waitcnt lgkmcnt(2)
	v_lshlrev_b32_e32 v166, 16, v90
	v_and_b32_e32 v167, 0xffff0000, v90
	v_lshlrev_b32_e32 v90, 16, v91
	v_and_b32_e32 v91, 0xffff0000, v91
	s_waitcnt lgkmcnt(1)
	v_lshlrev_b32_e32 v172, 16, v70
	s_waitcnt vmcnt(27)
	v_pk_fma_f32 v[88:89], v[0:1], v[88:89], v[12:13]
	v_and_b32_e32 v173, 0xffff0000, v70
	v_pk_fma_f32 v[72:73], v[2:3], v[116:117], v[88:89]
	v_pk_fma_f32 v[116:117], v[0:1], v[116:117], v[12:13]
	v_pk_fma_f32 v[72:73], v[4:5], v[120:121], v[72:73]
	v_pk_fma_f32 v[116:117], v[2:3], v[120:121], v[116:117]
	v_pk_fma_f32 v[120:121], v[0:1], v[120:121], v[12:13]
	v_pk_fma_f32 v[72:73], v[6:7], v[130:131], v[72:73]
	v_pk_fma_f32 v[116:117], v[4:5], v[130:131], v[116:117]
	v_pk_fma_f32 v[120:121], v[2:3], v[130:131], v[120:121]
	v_pk_fma_f32 v[130:131], v[0:1], v[130:131], v[12:13]
	s_waitcnt vmcnt(24)
	v_pk_fma_f32 v[72:73], v[24:25], v[136:137], v[72:73]
	v_pk_fma_f32 v[116:117], v[6:7], v[136:137], v[116:117]
	v_pk_fma_f32 v[120:121], v[4:5], v[136:137], v[120:121]
	v_pk_fma_f32 v[130:131], v[2:3], v[136:137], v[130:131]
	v_pk_fma_f32 v[136:137], v[0:1], v[136:137], v[12:13]
	v_pk_fma_f32 v[72:73], v[14:15], v[144:145], v[72:73]
	v_pk_fma_f32 v[116:117], v[24:25], v[144:145], v[116:117]
	v_pk_fma_f32 v[120:121], v[6:7], v[144:145], v[120:121]
	v_pk_fma_f32 v[130:131], v[4:5], v[144:145], v[130:131]
	v_pk_fma_f32 v[136:137], v[2:3], v[144:145], v[136:137]
	v_pk_fma_f32 v[144:145], v[0:1], v[144:145], v[12:13]
	v_pk_fma_f32 v[72:73], v[16:17], v[148:149], v[72:73]
	v_pk_fma_f32 v[116:117], v[14:15], v[148:149], v[116:117]
	v_pk_fma_f32 v[120:121], v[24:25], v[148:149], v[120:121]
	v_pk_fma_f32 v[130:131], v[6:7], v[148:149], v[130:131]
	v_pk_fma_f32 v[136:137], v[4:5], v[148:149], v[136:137]
	v_pk_fma_f32 v[144:145], v[2:3], v[148:149], v[144:145]
	v_pk_fma_f32 v[148:149], v[0:1], v[148:149], v[12:13]
	s_waitcnt vmcnt(20)
	v_pk_fma_f32 v[72:73], v[36:37], v[146:147], v[72:73]
	v_pk_fma_f32 v[116:117], v[16:17], v[146:147], v[116:117]
	v_pk_fma_f32 v[120:121], v[14:15], v[146:147], v[120:121]
	v_pk_fma_f32 v[130:131], v[24:25], v[146:147], v[130:131]
	v_pk_fma_f32 v[136:137], v[6:7], v[146:147], v[136:137]
	v_pk_fma_f32 v[144:145], v[4:5], v[146:147], v[144:145]
	v_pk_fma_f32 v[148:149], v[2:3], v[146:147], v[148:149]
	v_pk_fma_f32 v[146:147], v[0:1], v[146:147], v[12:13]
	v_pk_fma_f32 v[72:73], v[18:19], v[140:141], v[72:73]
	v_pk_fma_f32 v[116:117], v[36:37], v[140:141], v[116:117]
	v_pk_fma_f32 v[130:131], v[14:15], v[140:141], v[130:131]
	v_pk_fma_f32 v[144:145], v[6:7], v[140:141], v[144:145]
	v_pk_fma_f32 v[146:147], v[2:3], v[140:141], v[146:147]
	v_pk_fma_f32 v[72:73], v[20:21], v[134:135], v[72:73]
	v_pk_fma_f32 v[116:117], v[18:19], v[134:135], v[116:117]
	v_pk_fma_f32 v[120:121], v[16:17], v[140:141], v[120:121]
	v_pk_fma_f32 v[130:131], v[16:17], v[134:135], v[130:131]
	v_pk_fma_f32 v[136:137], v[24:25], v[140:141], v[136:137]
	v_pk_fma_f32 v[144:145], v[24:25], v[134:135], v[144:145]
	v_pk_fma_f32 v[148:149], v[4:5], v[140:141], v[148:149]
	v_pk_fma_f32 v[146:147], v[4:5], v[134:135], v[146:147]
	v_pk_fma_f32 v[140:141], v[0:1], v[140:141], v[12:13]
	v_pk_fma_f32 v[72:73], v[22:23], v[128:129], v[72:73]
	v_pk_fma_f32 v[116:117], v[20:21], v[128:129], v[116:117]
	v_pk_fma_f32 v[120:121], v[36:37], v[134:135], v[120:121]
	v_pk_fma_f32 v[130:131], v[36:37], v[128:129], v[130:131]
	v_pk_fma_f32 v[136:137], v[14:15], v[134:135], v[136:137]
	v_pk_fma_f32 v[144:145], v[14:15], v[128:129], v[144:145]
	v_pk_fma_f32 v[148:149], v[6:7], v[134:135], v[148:149]
	v_pk_fma_f32 v[146:147], v[6:7], v[128:129], v[146:147]
	v_pk_fma_f32 v[140:141], v[2:3], v[134:135], v[140:141]
	v_pk_fma_f32 v[134:135], v[0:1], v[134:135], v[12:13]
	s_waitcnt vmcnt(18)
	v_pk_fma_f32 v[72:73], v[32:33], v[122:123], v[72:73]
	v_pk_fma_f32 v[116:117], v[22:23], v[122:123], v[116:117]
	v_pk_fma_f32 v[120:121], v[18:19], v[128:129], v[120:121]
	v_pk_fma_f32 v[130:131], v[18:19], v[122:123], v[130:131]
	v_pk_fma_f32 v[136:137], v[16:17], v[128:129], v[136:137]
	v_pk_fma_f32 v[144:145], v[16:17], v[122:123], v[144:145]
	v_pk_fma_f32 v[148:149], v[24:25], v[128:129], v[148:149]
	v_pk_fma_f32 v[146:147], v[24:25], v[122:123], v[146:147]
	v_pk_fma_f32 v[140:141], v[4:5], v[128:129], v[140:141]
	v_pk_fma_f32 v[134:135], v[2:3], v[128:129], v[134:135]
	v_pk_fma_f32 v[128:129], v[0:1], v[128:129], v[12:13]
	s_waitcnt vmcnt(17)
	v_pk_fma_f32 v[72:73], v[34:35], v[114:115], v[72:73]
	v_pk_fma_f32 v[116:117], v[32:33], v[114:115], v[116:117]
	v_pk_fma_f32 v[120:121], v[20:21], v[122:123], v[120:121]
	v_pk_fma_f32 v[130:131], v[20:21], v[114:115], v[130:131]
	v_pk_fma_f32 v[136:137], v[36:37], v[122:123], v[136:137]
	v_pk_fma_f32 v[144:145], v[36:37], v[114:115], v[144:145]
	v_pk_fma_f32 v[148:149], v[14:15], v[122:123], v[148:149]
	v_pk_fma_f32 v[146:147], v[14:15], v[114:115], v[146:147]
	v_pk_fma_f32 v[140:141], v[6:7], v[122:123], v[140:141]
	v_pk_fma_f32 v[134:135], v[4:5], v[122:123], v[134:135]
	v_pk_fma_f32 v[128:129], v[2:3], v[122:123], v[128:129]
	v_pk_fma_f32 v[122:123], v[0:1], v[122:123], v[12:13]
	v_pk_fma_f32 v[72:73], v[26:27], v[110:111], v[72:73]
	v_lshlrev_b32_e32 v88, 16, v86
	v_and_b32_e32 v89, 0xffff0000, v86
	v_pk_fma_f32 v[116:117], v[34:35], v[110:111], v[116:117]
	v_pk_fma_f32 v[120:121], v[22:23], v[114:115], v[120:121]
	v_pk_fma_f32 v[130:131], v[22:23], v[110:111], v[130:131]
	v_pk_fma_f32 v[136:137], v[18:19], v[114:115], v[136:137]
	v_pk_fma_f32 v[144:145], v[18:19], v[110:111], v[144:145]
	v_pk_fma_f32 v[148:149], v[16:17], v[114:115], v[148:149]
	v_pk_fma_f32 v[146:147], v[16:17], v[110:111], v[146:147]
	v_pk_fma_f32 v[140:141], v[24:25], v[114:115], v[140:141]
	v_pk_fma_f32 v[134:135], v[6:7], v[114:115], v[134:135]
	v_pk_fma_f32 v[128:129], v[4:5], v[114:115], v[128:129]
	v_pk_fma_f32 v[122:123], v[2:3], v[114:115], v[122:123]
	v_pk_fma_f32 v[114:115], v[0:1], v[114:115], v[12:13]
	s_waitcnt vmcnt(14)
	v_pk_fma_f32 v[74:75], v[52:53], v[88:89], v[72:73]
	v_lshlrev_b32_e32 v72, 16, v87
	v_and_b32_e32 v73, 0xffff0000, v87
	v_pk_fma_f32 v[116:117], v[26:27], v[88:89], v[116:117]
	v_pk_fma_f32 v[120:121], v[32:33], v[110:111], v[120:121]
	v_pk_fma_f32 v[130:131], v[32:33], v[88:89], v[130:131]
	v_pk_fma_f32 v[136:137], v[20:21], v[110:111], v[136:137]
	v_pk_fma_f32 v[144:145], v[20:21], v[88:89], v[144:145]
	v_pk_fma_f32 v[148:149], v[36:37], v[110:111], v[148:149]
	v_pk_fma_f32 v[146:147], v[36:37], v[88:89], v[146:147]
	v_pk_fma_f32 v[140:141], v[14:15], v[110:111], v[140:141]
	v_pk_fma_f32 v[134:135], v[24:25], v[110:111], v[134:135]
	v_pk_fma_f32 v[128:129], v[6:7], v[110:111], v[128:129]
	v_pk_fma_f32 v[122:123], v[4:5], v[110:111], v[122:123]
	v_pk_fma_f32 v[114:115], v[2:3], v[110:111], v[114:115]
	v_pk_fma_f32 v[110:111], v[0:1], v[110:111], v[12:13]
	s_waitcnt vmcnt(13)
	v_pk_fma_f32 v[76:77], v[54:55], v[72:73], v[74:75]
	v_lshlrev_b32_e32 v74, 16, v92
	v_and_b32_e32 v75, 0xffff0000, v92
	v_pk_fma_f32 v[116:117], v[52:53], v[72:73], v[116:117]
	v_pk_fma_f32 v[120:121], v[34:35], v[88:89], v[120:121]
	v_pk_fma_f32 v[130:131], v[34:35], v[72:73], v[130:131]
	v_pk_fma_f32 v[136:137], v[22:23], v[88:89], v[136:137]
	v_pk_fma_f32 v[144:145], v[22:23], v[72:73], v[144:145]
	v_pk_fma_f32 v[148:149], v[18:19], v[88:89], v[148:149]
	v_pk_fma_f32 v[146:147], v[18:19], v[72:73], v[146:147]
	v_pk_fma_f32 v[140:141], v[16:17], v[88:89], v[140:141]
	v_pk_fma_f32 v[134:135], v[14:15], v[88:89], v[134:135]
	v_pk_fma_f32 v[128:129], v[24:25], v[88:89], v[128:129]
	v_pk_fma_f32 v[122:123], v[6:7], v[88:89], v[122:123]
	v_pk_fma_f32 v[114:115], v[4:5], v[88:89], v[114:115]
	v_pk_fma_f32 v[110:111], v[2:3], v[88:89], v[110:111]
	v_pk_fma_f32 v[88:89], v[0:1], v[88:89], v[12:13]
	v_pk_fma_f32 v[0:1], v[0:1], v[72:73], v[12:13]
	v_pk_fma_f32 v[78:79], v[28:29], v[74:75], v[76:77]
	v_lshlrev_b32_e32 v76, 16, v93
	v_and_b32_e32 v77, 0xffff0000, v93
	v_pk_fma_f32 v[116:117], v[54:55], v[74:75], v[116:117]
	v_pk_fma_f32 v[130:131], v[26:27], v[74:75], v[130:131]
	v_pk_fma_f32 v[144:145], v[32:33], v[74:75], v[144:145]
	v_pk_fma_f32 v[146:147], v[20:21], v[74:75], v[146:147]
	v_pk_fma_f32 v[0:1], v[2:3], v[74:75], v[0:1]
	v_pk_fma_f32 v[80:81], v[30:31], v[76:77], v[78:79]
	v_lshlrev_b32_e32 v78, 16, v94
	v_and_b32_e32 v79, 0xffff0000, v94
	v_pk_fma_f32 v[116:117], v[28:29], v[76:77], v[116:117]
	v_pk_fma_f32 v[130:131], v[52:53], v[76:77], v[130:131]
	v_pk_fma_f32 v[144:145], v[34:35], v[76:77], v[144:145]
	v_pk_fma_f32 v[146:147], v[22:23], v[76:77], v[146:147]
	v_pk_fma_f32 v[88:89], v[2:3], v[72:73], v[88:89]
	v_pk_fma_f32 v[0:1], v[4:5], v[76:77], v[0:1]
	s_waitcnt vmcnt(10)
	v_pk_fma_f32 v[82:83], v[56:57], v[78:79], v[80:81]
	v_lshlrev_b32_e32 v80, 16, v95
	v_and_b32_e32 v81, 0xffff0000, v95
	v_pk_fma_f32 v[116:117], v[30:31], v[78:79], v[116:117]
	v_pk_fma_f32 v[130:131], v[54:55], v[78:79], v[130:131]
	v_pk_fma_f32 v[144:145], v[26:27], v[78:79], v[144:145]
	v_pk_fma_f32 v[146:147], v[32:33], v[78:79], v[146:147]
	v_pk_fma_f32 v[110:111], v[4:5], v[72:73], v[110:111]
	v_pk_fma_f32 v[88:89], v[4:5], v[74:75], v[88:89]
	v_pk_fma_f32 v[0:1], v[6:7], v[78:79], v[0:1]
	s_waitcnt vmcnt(9)
	v_pk_fma_f32 v[84:85], v[58:59], v[80:81], v[82:83]
	v_lshlrev_b32_e32 v82, 16, v96
	v_and_b32_e32 v83, 0xffff0000, v96
	v_pk_fma_f32 v[116:117], v[56:57], v[80:81], v[116:117]
	v_pk_fma_f32 v[130:131], v[28:29], v[80:81], v[130:131]
	v_pk_fma_f32 v[144:145], v[52:53], v[80:81], v[144:145]
	v_pk_fma_f32 v[146:147], v[34:35], v[80:81], v[146:147]
	v_pk_fma_f32 v[114:115], v[6:7], v[72:73], v[114:115]
	v_pk_fma_f32 v[110:111], v[6:7], v[74:75], v[110:111]
	v_pk_fma_f32 v[88:89], v[6:7], v[76:77], v[88:89]
	v_pk_fma_f32 v[0:1], v[24:25], v[80:81], v[0:1]
	s_waitcnt vmcnt(8)
	v_pk_fma_f32 v[86:87], v[60:61], v[82:83], v[84:85]
	v_lshlrev_b32_e32 v84, 16, v97
	v_and_b32_e32 v85, 0xffff0000, v97
	v_pk_fma_f32 v[116:117], v[58:59], v[82:83], v[116:117]
	v_pk_fma_f32 v[130:131], v[30:31], v[82:83], v[130:131]
	v_pk_fma_f32 v[144:145], v[54:55], v[82:83], v[144:145]
	v_pk_fma_f32 v[146:147], v[26:27], v[82:83], v[146:147]
	v_pk_fma_f32 v[122:123], v[24:25], v[72:73], v[122:123]
	v_pk_fma_f32 v[114:115], v[24:25], v[74:75], v[114:115]
	v_pk_fma_f32 v[110:111], v[24:25], v[76:77], v[110:111]
	v_pk_fma_f32 v[88:89], v[24:25], v[78:79], v[88:89]
	v_pk_fma_f32 v[0:1], v[14:15], v[82:83], v[0:1]
	v_pk_fma_f32 v[92:93], v[38:39], v[84:85], v[86:87]
	v_lshlrev_b32_e32 v86, 16, v98
	v_and_b32_e32 v87, 0xffff0000, v98
	v_pk_fma_f32 v[116:117], v[60:61], v[84:85], v[116:117]
	v_pk_fma_f32 v[130:131], v[56:57], v[84:85], v[130:131]
	v_pk_fma_f32 v[144:145], v[28:29], v[84:85], v[144:145]
	v_pk_fma_f32 v[146:147], v[52:53], v[84:85], v[146:147]
	v_pk_fma_f32 v[128:129], v[14:15], v[72:73], v[128:129]
	v_pk_fma_f32 v[122:123], v[14:15], v[74:75], v[122:123]
	v_pk_fma_f32 v[114:115], v[14:15], v[76:77], v[114:115]
	v_pk_fma_f32 v[110:111], v[14:15], v[78:79], v[110:111]
	v_pk_fma_f32 v[88:89], v[14:15], v[80:81], v[88:89]
	v_pk_fma_f32 v[0:1], v[16:17], v[84:85], v[0:1]
	v_pk_fma_f32 v[94:95], v[40:41], v[86:87], v[92:93]
	v_lshlrev_b32_e32 v92, 16, v99
	v_and_b32_e32 v93, 0xffff0000, v99
	v_pk_fma_f32 v[116:117], v[38:39], v[86:87], v[116:117]
	v_pk_fma_f32 v[130:131], v[58:59], v[86:87], v[130:131]
	v_pk_fma_f32 v[144:145], v[30:31], v[86:87], v[144:145]
	v_pk_fma_f32 v[146:147], v[54:55], v[86:87], v[146:147]
	v_pk_fma_f32 v[134:135], v[16:17], v[72:73], v[134:135]
	v_pk_fma_f32 v[128:129], v[16:17], v[74:75], v[128:129]
	v_pk_fma_f32 v[122:123], v[16:17], v[76:77], v[122:123]
	v_pk_fma_f32 v[114:115], v[16:17], v[78:79], v[114:115]
	v_pk_fma_f32 v[110:111], v[16:17], v[80:81], v[110:111]
	v_pk_fma_f32 v[88:89], v[16:17], v[82:83], v[88:89]
	v_pk_fma_f32 v[0:1], v[36:37], v[86:87], v[0:1]
	s_waitcnt vmcnt(3)
	v_pk_fma_f32 v[96:97], v[66:67], v[92:93], v[94:95]
	v_lshlrev_b32_e32 v94, 16, v100
	v_and_b32_e32 v95, 0xffff0000, v100
	v_pk_fma_f32 v[116:117], v[40:41], v[92:93], v[116:117]
	v_pk_fma_f32 v[130:131], v[60:61], v[92:93], v[130:131]
	v_pk_fma_f32 v[144:145], v[56:57], v[92:93], v[144:145]
	v_pk_fma_f32 v[146:147], v[28:29], v[92:93], v[146:147]
	v_pk_fma_f32 v[140:141], v[36:37], v[72:73], v[140:141]
	v_pk_fma_f32 v[134:135], v[36:37], v[74:75], v[134:135]
	v_pk_fma_f32 v[128:129], v[36:37], v[76:77], v[128:129]
	v_pk_fma_f32 v[122:123], v[36:37], v[78:79], v[122:123]
	v_pk_fma_f32 v[114:115], v[36:37], v[80:81], v[114:115]
	v_pk_fma_f32 v[110:111], v[36:37], v[82:83], v[110:111]
	v_pk_fma_f32 v[88:89], v[36:37], v[84:85], v[88:89]
	v_pk_fma_f32 v[0:1], v[18:19], v[92:93], v[0:1]
	v_pk_fma_f32 v[98:99], v[42:43], v[94:95], v[96:97]
	v_lshlrev_b32_e32 v96, 16, v101
	v_and_b32_e32 v97, 0xffff0000, v101
	v_pk_fma_f32 v[116:117], v[66:67], v[94:95], v[116:117]
	v_pk_fma_f32 v[130:131], v[38:39], v[94:95], v[130:131]
	v_pk_fma_f32 v[144:145], v[58:59], v[94:95], v[144:145]
	v_pk_fma_f32 v[146:147], v[30:31], v[94:95], v[146:147]
	v_pk_fma_f32 v[140:141], v[18:19], v[74:75], v[140:141]
	v_pk_fma_f32 v[134:135], v[18:19], v[76:77], v[134:135]
	v_pk_fma_f32 v[128:129], v[18:19], v[78:79], v[128:129]
	v_pk_fma_f32 v[122:123], v[18:19], v[80:81], v[122:123]
	v_pk_fma_f32 v[114:115], v[18:19], v[82:83], v[114:115]
	v_pk_fma_f32 v[110:111], v[18:19], v[84:85], v[110:111]
	v_pk_fma_f32 v[88:89], v[18:19], v[86:87], v[88:89]
	v_pk_fma_f32 v[0:1], v[20:21], v[94:95], v[0:1]
	v_lshlrev_b32_e32 v100, 16, v102
	v_and_b32_e32 v101, 0xffff0000, v102
	v_pk_fma_f32 v[116:117], v[42:43], v[96:97], v[116:117]
	v_pk_fma_f32 v[130:131], v[40:41], v[96:97], v[130:131]
	v_pk_fma_f32 v[144:145], v[60:61], v[96:97], v[144:145]
	v_pk_fma_f32 v[148:149], v[20:21], v[72:73], v[148:149]
	v_pk_fma_f32 v[146:147], v[56:57], v[96:97], v[146:147]
	v_pk_fma_f32 v[140:141], v[20:21], v[76:77], v[140:141]
	v_pk_fma_f32 v[134:135], v[20:21], v[78:79], v[134:135]
	v_pk_fma_f32 v[128:129], v[20:21], v[80:81], v[128:129]
	v_pk_fma_f32 v[122:123], v[20:21], v[82:83], v[122:123]
	v_pk_fma_f32 v[114:115], v[20:21], v[84:85], v[114:115]
	v_pk_fma_f32 v[110:111], v[20:21], v[86:87], v[110:111]
	v_pk_fma_f32 v[88:89], v[20:21], v[92:93], v[88:89]
	v_pk_fma_f32 v[0:1], v[22:23], v[96:97], v[0:1]
	v_lshlrev_b32_e32 v102, 16, v103
	v_and_b32_e32 v103, 0xffff0000, v103
	v_pk_fma_f32 v[116:117], v[44:45], v[100:101], v[116:117]
	v_pk_fma_f32 v[130:131], v[66:67], v[100:101], v[130:131]
	v_pk_fma_f32 v[144:145], v[38:39], v[100:101], v[144:145]
	v_pk_fma_f32 v[148:149], v[22:23], v[74:75], v[148:149]
	v_pk_fma_f32 v[146:147], v[58:59], v[100:101], v[146:147]
	v_pk_fma_f32 v[140:141], v[22:23], v[78:79], v[140:141]
	v_pk_fma_f32 v[134:135], v[22:23], v[80:81], v[134:135]
	v_pk_fma_f32 v[128:129], v[22:23], v[82:83], v[128:129]
	v_pk_fma_f32 v[122:123], v[22:23], v[84:85], v[122:123]
	v_pk_fma_f32 v[114:115], v[22:23], v[86:87], v[114:115]
	v_pk_fma_f32 v[110:111], v[22:23], v[92:93], v[110:111]
	v_pk_fma_f32 v[88:89], v[22:23], v[94:95], v[88:89]
	v_pk_fma_f32 v[0:1], v[32:33], v[100:101], v[0:1]
	v_pk_fma_f32 v[116:117], v[46:47], v[102:103], v[116:117]
	v_pk_fma_f32 v[130:131], v[42:43], v[102:103], v[130:131]
	v_pk_fma_f32 v[136:137], v[32:33], v[72:73], v[136:137]
	v_pk_fma_f32 v[144:145], v[40:41], v[102:103], v[144:145]
	v_pk_fma_f32 v[148:149], v[32:33], v[76:77], v[148:149]
	v_pk_fma_f32 v[146:147], v[60:61], v[102:103], v[146:147]
	v_pk_fma_f32 v[140:141], v[32:33], v[80:81], v[140:141]
	v_pk_fma_f32 v[134:135], v[32:33], v[82:83], v[134:135]
	v_pk_fma_f32 v[128:129], v[32:33], v[84:85], v[128:129]
	v_pk_fma_f32 v[122:123], v[32:33], v[86:87], v[122:123]
	v_pk_fma_f32 v[114:115], v[32:33], v[92:93], v[114:115]
	v_pk_fma_f32 v[110:111], v[32:33], v[94:95], v[110:111]
	v_pk_fma_f32 v[88:89], v[32:33], v[96:97], v[88:89]
	v_pk_fma_f32 v[0:1], v[34:35], v[102:103], v[0:1]
	v_pk_fma_f32 v[116:117], v[48:49], v[104:105], v[116:117]
	v_pk_fma_f32 v[130:131], v[44:45], v[104:105], v[130:131]
	v_pk_fma_f32 v[136:137], v[34:35], v[74:75], v[136:137]
	v_pk_fma_f32 v[144:145], v[66:67], v[104:105], v[144:145]
	v_pk_fma_f32 v[148:149], v[34:35], v[78:79], v[148:149]
	v_pk_fma_f32 v[146:147], v[38:39], v[104:105], v[146:147]
	v_pk_fma_f32 v[140:141], v[34:35], v[82:83], v[140:141]
	v_pk_fma_f32 v[134:135], v[34:35], v[84:85], v[134:135]
	v_pk_fma_f32 v[128:129], v[34:35], v[86:87], v[128:129]
	v_pk_fma_f32 v[122:123], v[34:35], v[92:93], v[122:123]
	v_pk_fma_f32 v[114:115], v[34:35], v[94:95], v[114:115]
	v_pk_fma_f32 v[110:111], v[34:35], v[96:97], v[110:111]
	v_pk_fma_f32 v[88:89], v[34:35], v[100:101], v[88:89]
	v_pk_fma_f32 v[0:1], v[26:27], v[104:105], v[0:1]
	s_waitcnt vmcnt(2)
	v_pk_fma_f32 v[116:117], v[62:63], v[106:107], v[116:117]
	v_pk_fma_f32 v[120:121], v[26:27], v[72:73], v[120:121]
	v_pk_fma_f32 v[130:131], v[46:47], v[106:107], v[130:131]
	v_pk_fma_f32 v[136:137], v[26:27], v[76:77], v[136:137]
	v_pk_fma_f32 v[144:145], v[42:43], v[106:107], v[144:145]
	v_pk_fma_f32 v[148:149], v[26:27], v[80:81], v[148:149]
	v_pk_fma_f32 v[146:147], v[40:41], v[106:107], v[146:147]
	v_pk_fma_f32 v[140:141], v[26:27], v[84:85], v[140:141]
	v_pk_fma_f32 v[134:135], v[26:27], v[86:87], v[134:135]
	v_pk_fma_f32 v[128:129], v[26:27], v[92:93], v[128:129]
	v_pk_fma_f32 v[122:123], v[26:27], v[94:95], v[122:123]
	v_pk_fma_f32 v[114:115], v[26:27], v[96:97], v[114:115]
	v_pk_fma_f32 v[110:111], v[26:27], v[100:101], v[110:111]
	v_pk_fma_f32 v[88:89], v[26:27], v[102:103], v[88:89]
	v_pk_fma_f32 v[0:1], v[52:53], v[106:107], v[0:1]
	s_waitcnt vmcnt(1)
	v_pk_fma_f32 v[124:125], v[64:65], v[108:109], v[116:117]
	v_lshlrev_b32_e32 v116, 16, v113
	v_and_b32_e32 v117, 0xffff0000, v113
	v_pk_fma_f32 v[120:121], v[52:53], v[74:75], v[120:121]
	v_pk_fma_f32 v[130:131], v[48:49], v[108:109], v[130:131]
	v_pk_fma_f32 v[136:137], v[52:53], v[78:79], v[136:137]
	v_pk_fma_f32 v[144:145], v[44:45], v[108:109], v[144:145]
	v_pk_fma_f32 v[148:149], v[52:53], v[82:83], v[148:149]
	v_pk_fma_f32 v[146:147], v[66:67], v[108:109], v[146:147]
	v_pk_fma_f32 v[140:141], v[52:53], v[86:87], v[140:141]
	v_pk_fma_f32 v[134:135], v[52:53], v[92:93], v[134:135]
	v_pk_fma_f32 v[128:129], v[52:53], v[94:95], v[128:129]
	v_pk_fma_f32 v[122:123], v[52:53], v[96:97], v[122:123]
	v_pk_fma_f32 v[114:115], v[52:53], v[100:101], v[114:115]
	v_pk_fma_f32 v[110:111], v[52:53], v[102:103], v[110:111]
	v_pk_fma_f32 v[88:89], v[52:53], v[104:105], v[88:89]
	v_pk_fma_f32 v[0:1], v[54:55], v[108:109], v[0:1]
	s_waitcnt vmcnt(0)
	v_pk_fma_f32 v[112:113], v[50:51], v[116:117], v[124:125]
	v_pk_fma_f32 v[120:121], v[54:55], v[76:77], v[120:121]
	v_lshlrev_b32_e32 v124, 16, v126
	v_and_b32_e32 v125, 0xffff0000, v126
	v_pk_fma_f32 v[130:131], v[62:63], v[116:117], v[130:131]
	v_pk_fma_f32 v[136:137], v[54:55], v[80:81], v[136:137]
	v_pk_fma_f32 v[144:145], v[46:47], v[116:117], v[144:145]
	v_pk_fma_f32 v[148:149], v[54:55], v[84:85], v[148:149]
	v_pk_fma_f32 v[146:147], v[42:43], v[116:117], v[146:147]
	v_pk_fma_f32 v[140:141], v[54:55], v[92:93], v[140:141]
	v_pk_fma_f32 v[134:135], v[54:55], v[94:95], v[134:135]
	v_pk_fma_f32 v[128:129], v[54:55], v[96:97], v[128:129]
	v_pk_fma_f32 v[122:123], v[54:55], v[100:101], v[122:123]
	v_pk_fma_f32 v[114:115], v[54:55], v[102:103], v[114:115]
	v_pk_fma_f32 v[110:111], v[54:55], v[104:105], v[110:111]
	v_pk_fma_f32 v[88:89], v[54:55], v[106:107], v[88:89]
	v_pk_fma_f32 v[0:1], v[28:29], v[116:117], v[0:1]
	v_pk_fma_f32 v[120:121], v[28:29], v[78:79], v[120:121]
	v_pk_fma_f32 v[138:139], v[64:65], v[124:125], v[130:131]
	v_lshlrev_b32_e32 v130, 16, v127
	v_and_b32_e32 v131, 0xffff0000, v127
	v_pk_fma_f32 v[136:137], v[28:29], v[82:83], v[136:137]
	v_pk_fma_f32 v[144:145], v[48:49], v[124:125], v[144:145]
	v_pk_fma_f32 v[148:149], v[28:29], v[86:87], v[148:149]
	v_pk_fma_f32 v[146:147], v[44:45], v[124:125], v[146:147]
	v_pk_fma_f32 v[140:141], v[28:29], v[94:95], v[140:141]
	v_pk_fma_f32 v[134:135], v[28:29], v[96:97], v[134:135]
	v_pk_fma_f32 v[128:129], v[28:29], v[100:101], v[128:129]
	v_pk_fma_f32 v[122:123], v[28:29], v[102:103], v[122:123]
	v_pk_fma_f32 v[114:115], v[28:29], v[104:105], v[114:115]
	v_pk_fma_f32 v[110:111], v[28:29], v[106:107], v[110:111]
	v_pk_fma_f32 v[88:89], v[28:29], v[108:109], v[88:89]
	v_pk_fma_f32 v[0:1], v[30:31], v[124:125], v[0:1]
	v_pk_fma_f32 v[120:121], v[30:31], v[80:81], v[120:121]
	v_pk_fma_f32 v[126:127], v[50:51], v[130:131], v[138:139]
	v_pk_fma_f32 v[136:137], v[30:31], v[84:85], v[136:137]
	v_lshlrev_b32_e32 v138, 16, v142
	v_and_b32_e32 v139, 0xffff0000, v142
	v_pk_fma_f32 v[144:145], v[62:63], v[130:131], v[144:145]
	v_pk_fma_f32 v[148:149], v[30:31], v[92:93], v[148:149]
	v_pk_fma_f32 v[146:147], v[46:47], v[130:131], v[146:147]
	v_pk_fma_f32 v[140:141], v[30:31], v[96:97], v[140:141]
	v_pk_fma_f32 v[134:135], v[30:31], v[100:101], v[134:135]
	v_pk_fma_f32 v[128:129], v[30:31], v[102:103], v[128:129]
	v_pk_fma_f32 v[122:123], v[30:31], v[104:105], v[122:123]
	v_pk_fma_f32 v[114:115], v[30:31], v[106:107], v[114:115]
	v_pk_fma_f32 v[110:111], v[30:31], v[108:109], v[110:111]
	v_pk_fma_f32 v[88:89], v[30:31], v[116:117], v[88:89]
	v_pk_fma_f32 v[0:1], v[56:57], v[130:131], v[0:1]
	v_pk_fma_f32 v[120:121], v[56:57], v[82:83], v[120:121]
	v_pk_fma_f32 v[136:137], v[56:57], v[86:87], v[136:137]
	v_pk_fma_f32 v[150:151], v[64:65], v[138:139], v[144:145]
	v_lshlrev_b32_e32 v144, 16, v143
	v_and_b32_e32 v145, 0xffff0000, v143
	v_pk_fma_f32 v[148:149], v[56:57], v[94:95], v[148:149]
	v_pk_fma_f32 v[146:147], v[48:49], v[138:139], v[146:147]
	v_pk_fma_f32 v[140:141], v[56:57], v[100:101], v[140:141]
	v_pk_fma_f32 v[134:135], v[56:57], v[102:103], v[134:135]
	v_pk_fma_f32 v[128:129], v[56:57], v[104:105], v[128:129]
	v_pk_fma_f32 v[122:123], v[56:57], v[106:107], v[122:123]
	v_pk_fma_f32 v[114:115], v[56:57], v[108:109], v[114:115]
	v_pk_fma_f32 v[110:111], v[56:57], v[116:117], v[110:111]
	v_pk_fma_f32 v[88:89], v[56:57], v[124:125], v[88:89]
	v_pk_fma_f32 v[0:1], v[58:59], v[138:139], v[0:1]
	v_pk_fma_f32 v[120:121], v[58:59], v[84:85], v[120:121]
	v_pk_fma_f32 v[136:137], v[58:59], v[92:93], v[136:137]
	v_pk_fma_f32 v[142:143], v[50:51], v[144:145], v[150:151]
	v_pk_fma_f32 v[148:149], v[58:59], v[96:97], v[148:149]
	v_lshlrev_b32_e32 v150, 16, v132
	v_and_b32_e32 v151, 0xffff0000, v132
	v_pk_fma_f32 v[146:147], v[62:63], v[144:145], v[146:147]
	v_pk_fma_f32 v[140:141], v[58:59], v[102:103], v[140:141]
	v_pk_fma_f32 v[134:135], v[58:59], v[104:105], v[134:135]
	v_pk_fma_f32 v[128:129], v[58:59], v[106:107], v[128:129]
	v_pk_fma_f32 v[122:123], v[58:59], v[108:109], v[122:123]
	v_pk_fma_f32 v[114:115], v[58:59], v[116:117], v[114:115]
	v_pk_fma_f32 v[110:111], v[58:59], v[124:125], v[110:111]
	v_pk_fma_f32 v[88:89], v[58:59], v[130:131], v[88:89]
	v_pk_fma_f32 v[0:1], v[60:61], v[144:145], v[0:1]
	v_pk_fma_f32 v[120:121], v[60:61], v[86:87], v[120:121]
	v_pk_fma_f32 v[136:137], v[60:61], v[94:95], v[136:137]
	v_pk_fma_f32 v[148:149], v[60:61], v[100:101], v[148:149]
	v_pk_fma_f32 v[164:165], v[64:65], v[150:151], v[146:147]
	v_lshlrev_b32_e32 v146, 16, v133
	v_and_b32_e32 v147, 0xffff0000, v133
	v_pk_fma_f32 v[140:141], v[60:61], v[104:105], v[140:141]
	v_pk_fma_f32 v[134:135], v[60:61], v[106:107], v[134:135]
	v_pk_fma_f32 v[128:129], v[60:61], v[108:109], v[128:129]
	v_pk_fma_f32 v[122:123], v[60:61], v[116:117], v[122:123]
	v_pk_fma_f32 v[114:115], v[60:61], v[124:125], v[114:115]
	v_pk_fma_f32 v[110:111], v[60:61], v[130:131], v[110:111]
	v_pk_fma_f32 v[88:89], v[60:61], v[138:139], v[88:89]
	v_pk_fma_f32 v[0:1], v[38:39], v[150:151], v[0:1]
	v_pk_fma_f32 v[120:121], v[38:39], v[92:93], v[120:121]
	v_pk_fma_f32 v[136:137], v[38:39], v[96:97], v[136:137]
	v_pk_fma_f32 v[148:149], v[38:39], v[102:103], v[148:149]
	v_pk_fma_f32 v[132:133], v[50:51], v[146:147], v[164:165]
	v_pk_fma_f32 v[140:141], v[38:39], v[106:107], v[140:141]
	v_lshlrev_b32_e32 v164, 16, v118
	v_and_b32_e32 v165, 0xffff0000, v118
	v_pk_fma_f32 v[134:135], v[38:39], v[108:109], v[134:135]
	v_pk_fma_f32 v[128:129], v[38:39], v[116:117], v[128:129]
	v_pk_fma_f32 v[122:123], v[38:39], v[124:125], v[122:123]
	v_pk_fma_f32 v[114:115], v[38:39], v[130:131], v[114:115]
	v_pk_fma_f32 v[110:111], v[38:39], v[138:139], v[110:111]
	v_pk_fma_f32 v[88:89], v[38:39], v[144:145], v[88:89]
	v_pk_fma_f32 v[0:1], v[40:41], v[146:147], v[0:1]
	v_pk_fma_f32 v[120:121], v[40:41], v[94:95], v[120:121]
	v_pk_fma_f32 v[136:137], v[40:41], v[100:101], v[136:137]
	v_pk_fma_f32 v[148:149], v[40:41], v[104:105], v[148:149]
	v_pk_fma_f32 v[140:141], v[40:41], v[108:109], v[140:141]
	v_pk_fma_f32 v[134:135], v[40:41], v[116:117], v[134:135]
	v_lshlrev_b32_e32 v118, 16, v119
	v_and_b32_e32 v119, 0xffff0000, v119
	v_pk_fma_f32 v[128:129], v[40:41], v[124:125], v[128:129]
	v_pk_fma_f32 v[122:123], v[40:41], v[130:131], v[122:123]
	v_pk_fma_f32 v[114:115], v[40:41], v[138:139], v[114:115]
	v_pk_fma_f32 v[110:111], v[40:41], v[144:145], v[110:111]
	v_pk_fma_f32 v[88:89], v[40:41], v[150:151], v[88:89]
	v_pk_fma_f32 v[0:1], v[66:67], v[164:165], v[0:1]
	v_pk_fma_f32 v[120:121], v[66:67], v[96:97], v[120:121]
	v_pk_fma_f32 v[136:137], v[66:67], v[102:103], v[136:137]
	v_pk_fma_f32 v[148:149], v[66:67], v[106:107], v[148:149]
	v_pk_fma_f32 v[140:141], v[66:67], v[116:117], v[140:141]
	v_pk_fma_f32 v[134:135], v[66:67], v[124:125], v[134:135]
	v_pk_fma_f32 v[128:129], v[66:67], v[130:131], v[128:129]
	v_pk_fma_f32 v[122:123], v[66:67], v[138:139], v[122:123]
	v_pk_fma_f32 v[114:115], v[66:67], v[144:145], v[114:115]
	v_pk_fma_f32 v[110:111], v[66:67], v[150:151], v[110:111]
	v_pk_fma_f32 v[88:89], v[66:67], v[146:147], v[88:89]
	v_pk_fma_f32 v[0:1], v[42:43], v[118:119], v[0:1]
	v_pk_fma_f32 v[98:99], v[44:45], v[96:97], v[98:99]
	v_pk_fma_f32 v[120:121], v[42:43], v[100:101], v[120:121]
	v_pk_fma_f32 v[136:137], v[42:43], v[104:105], v[136:137]
	v_pk_fma_f32 v[148:149], v[42:43], v[108:109], v[148:149]
	v_pk_fma_f32 v[140:141], v[42:43], v[124:125], v[140:141]
	v_pk_fma_f32 v[134:135], v[42:43], v[130:131], v[134:135]
	v_pk_fma_f32 v[128:129], v[42:43], v[138:139], v[128:129]
	v_pk_fma_f32 v[122:123], v[42:43], v[144:145], v[122:123]
	v_pk_fma_f32 v[114:115], v[42:43], v[150:151], v[114:115]
	v_pk_fma_f32 v[110:111], v[42:43], v[146:147], v[110:111]
	v_pk_fma_f32 v[88:89], v[42:43], v[164:165], v[88:89]
	v_pk_fma_f32 v[0:1], v[44:45], v[166:167], v[0:1]
	v_pk_fma_f32 v[98:99], v[46:47], v[100:101], v[98:99]
	v_pk_fma_f32 v[120:121], v[44:45], v[102:103], v[120:121]
	v_pk_fma_f32 v[136:137], v[44:45], v[106:107], v[136:137]
	v_pk_fma_f32 v[148:149], v[44:45], v[116:117], v[148:149]
	v_pk_fma_f32 v[140:141], v[44:45], v[130:131], v[140:141]
	v_pk_fma_f32 v[134:135], v[44:45], v[138:139], v[134:135]
	v_pk_fma_f32 v[128:129], v[44:45], v[144:145], v[128:129]
	v_pk_fma_f32 v[122:123], v[44:45], v[150:151], v[122:123]
	v_pk_fma_f32 v[114:115], v[44:45], v[146:147], v[114:115]
	v_pk_fma_f32 v[110:111], v[44:45], v[164:165], v[110:111]
	v_pk_fma_f32 v[88:89], v[44:45], v[118:119], v[88:89]
	v_pk_fma_f32 v[0:1], v[46:47], v[90:91], v[0:1]
	v_pk_fma_f32 v[98:99], v[48:49], v[102:103], v[98:99]
	v_pk_fma_f32 v[120:121], v[46:47], v[104:105], v[120:121]
	v_pk_fma_f32 v[136:137], v[46:47], v[108:109], v[136:137]
	v_pk_fma_f32 v[148:149], v[46:47], v[124:125], v[148:149]
	v_pk_fma_f32 v[140:141], v[46:47], v[138:139], v[140:141]
	v_pk_fma_f32 v[134:135], v[46:47], v[144:145], v[134:135]
	v_pk_fma_f32 v[128:129], v[46:47], v[150:151], v[128:129]
	v_pk_fma_f32 v[122:123], v[46:47], v[146:147], v[122:123]
	v_pk_fma_f32 v[114:115], v[46:47], v[164:165], v[114:115]
	v_pk_fma_f32 v[110:111], v[46:47], v[118:119], v[110:111]
	v_lshlrev_b32_e32 v70, 16, v71
	v_and_b32_e32 v71, 0xffff0000, v71
	v_pk_fma_f32 v[88:89], v[46:47], v[166:167], v[88:89]
	v_pk_fma_f32 v[0:1], v[48:49], v[172:173], v[0:1]
	v_pk_fma_f32 v[98:99], v[62:63], v[104:105], v[98:99]
	v_pk_fma_f32 v[120:121], v[48:49], v[106:107], v[120:121]
	v_pk_fma_f32 v[136:137], v[48:49], v[116:117], v[136:137]
	v_pk_fma_f32 v[148:149], v[48:49], v[130:131], v[148:149]
	v_pk_fma_f32 v[140:141], v[48:49], v[144:145], v[140:141]
	v_pk_fma_f32 v[134:135], v[48:49], v[150:151], v[134:135]
	v_pk_fma_f32 v[128:129], v[48:49], v[146:147], v[128:129]
	v_pk_fma_f32 v[122:123], v[48:49], v[164:165], v[122:123]
	v_pk_fma_f32 v[114:115], v[48:49], v[118:119], v[114:115]
	v_pk_fma_f32 v[110:111], v[48:49], v[166:167], v[110:111]
	v_pk_fma_f32 v[88:89], v[48:49], v[90:91], v[88:89]
	s_waitcnt lgkmcnt(0)
	v_lshlrev_b32_e32 v174, 16, v68
	v_and_b32_e32 v175, 0xffff0000, v68
	v_pk_fma_f32 v[0:1], v[62:63], v[70:71], v[0:1]
	v_pk_fma_f32 v[98:99], v[64:65], v[106:107], v[98:99]
	v_pk_fma_f32 v[120:121], v[62:63], v[108:109], v[120:121]
	v_pk_fma_f32 v[136:137], v[62:63], v[124:125], v[136:137]
	v_pk_fma_f32 v[148:149], v[62:63], v[138:139], v[148:149]
	v_pk_fma_f32 v[140:141], v[62:63], v[150:151], v[140:141]
	v_pk_fma_f32 v[134:135], v[62:63], v[146:147], v[134:135]
	v_pk_fma_f32 v[128:129], v[62:63], v[164:165], v[128:129]
	v_pk_fma_f32 v[122:123], v[62:63], v[118:119], v[122:123]
	v_pk_fma_f32 v[114:115], v[62:63], v[166:167], v[114:115]
	v_pk_fma_f32 v[110:111], v[62:63], v[90:91], v[110:111]
	v_pk_fma_f32 v[88:89], v[62:63], v[172:173], v[88:89]
	v_pk_fma_f32 v[0:1], v[64:65], v[174:175], v[0:1]
	v_lshlrev_b32_e32 v2, 16, v69
	v_and_b32_e32 v3, 0xffff0000, v69
	v_pk_fma_f32 v[98:99], v[50:51], v[108:109], v[98:99]
	v_pk_fma_f32 v[120:121], v[64:65], v[116:117], v[120:121]
	v_pk_fma_f32 v[136:137], v[64:65], v[130:131], v[136:137]
	v_pk_fma_f32 v[148:149], v[64:65], v[144:145], v[148:149]
	v_pk_fma_f32 v[140:141], v[64:65], v[146:147], v[140:141]
	v_pk_fma_f32 v[134:135], v[64:65], v[164:165], v[134:135]
	v_pk_fma_f32 v[128:129], v[64:65], v[118:119], v[128:129]
	v_pk_fma_f32 v[122:123], v[64:65], v[166:167], v[122:123]
	v_pk_fma_f32 v[114:115], v[64:65], v[90:91], v[114:115]
	v_pk_fma_f32 v[110:111], v[64:65], v[172:173], v[110:111]
	v_pk_fma_f32 v[88:89], v[64:65], v[70:71], v[88:89]
	v_pk_fma_f32 v[0:1], v[50:51], v[2:3], v[0:1]
	v_pk_fma_f32 v[120:121], v[50:51], v[124:125], v[120:121]
	v_pk_fma_f32 v[136:137], v[50:51], v[138:139], v[136:137]
	v_pk_fma_f32 v[148:149], v[50:51], v[150:151], v[148:149]
	v_pk_fma_f32 v[140:141], v[50:51], v[164:165], v[140:141]
	v_pk_fma_f32 v[134:135], v[50:51], v[118:119], v[134:135]
	v_pk_fma_f32 v[128:129], v[50:51], v[166:167], v[128:129]
	v_pk_fma_f32 v[122:123], v[50:51], v[90:91], v[122:123]
	v_pk_fma_f32 v[114:115], v[50:51], v[172:173], v[114:115]
	v_pk_fma_f32 v[110:111], v[50:51], v[70:71], v[110:111]
	v_pk_fma_f32 v[88:89], v[50:51], v[174:175], v[88:89]
	ds_write2st64_b64 v161, v[98:99], v[112:113] offset0:96 offset1:98
	ds_write2st64_b64 v161, v[120:121], v[126:127] offset0:100 offset1:102
	ds_write2st64_b64 v161, v[136:137], v[142:143] offset0:104 offset1:106
	ds_write2st64_b64 v161, v[148:149], v[132:133] offset0:108 offset1:110
	ds_write2st64_b64 v161, v[140:141], v[134:135] offset0:112 offset1:114
	ds_write2st64_b64 v161, v[128:129], v[122:123] offset0:116 offset1:118
	ds_write2st64_b64 v161, v[114:115], v[110:111] offset0:120 offset1:122
	ds_write2st64_b64 v161, v[88:89], v[0:1] offset0:124 offset1:126
	v_add_u32_e32 v0, s1, v153
	s_waitcnt lgkmcnt(0)
	s_barrier
	ds_read_b128 v[12:15], v0 offset:49152
	s_addc_u32 s3, s45, s57
	s_add_u32 s4, s46, s56
	s_addc_u32 s5, s47, s57
	s_add_i32 s68, s68, s31
	s_waitcnt lgkmcnt(0)
	v_add_f32_e32 v0, v12, v13
	v_add_f32_e32 v0, v14, v0
	v_add_f32_e32 v0, v15, v0
	s_nop 1
	v_mov_b32_dpp v1, v0 quad_perm:[1,0,3,2] row_mask:0xf bank_mask:0xf
	s_waitcnt lgkmcnt(0)
	v_add_f32_e32 v11, v0, v1
	global_load_dwordx4 v[0:3], v162, s[2:3]
	global_load_dwordx4 v[4:7], v162, s[4:5]
	s_nop 1
	v_mov_b32_dpp v16, v11 quad_perm:[2,3,0,1] row_mask:0xf bank_mask:0xf
	s_add_i32 s2, s69, s0
	s_ashr_i32 s3, s2, 31
	s_lshl_b64 s[2:3], s[2:3], 9
	s_waitcnt lgkmcnt(0)
	v_add_f32_e32 v11, v11, v16
	s_nop 1
	v_mov_b32_dpp v16, v11 row_half_mirror row_mask:0xf bank_mask:0xf
	s_waitcnt lgkmcnt(0)
	v_add_f32_e32 v11, v11, v16
	s_nop 1
	v_mov_b32_dpp v16, v11 row_mirror row_mask:0xf bank_mask:0xf
	s_waitcnt lgkmcnt(0)
	v_add_f32_e32 v11, v11, v16
	v_mov_b32_e32 v16, v11
	s_nop 1
	v_permlane16_swap_b32_e32 v11, v16
	s_waitcnt lgkmcnt(0)
	v_add_f32_e32 v11, v11, v16
	v_mov_b32_e32 v16, v11
	s_nop 1
	v_permlane32_swap_b32_e32 v11, v16
	s_waitcnt lgkmcnt(0)
	v_add_f32_e32 v11, v11, v16
	v_fmac_f32_e32 v13, 0xbb800000, v11
	v_fmamk_f32 v15, v11, 0xbb800000, v15
	v_fmamk_f32 v14, v11, 0xbb800000, v14
	v_fmamk_f32 v12, v11, 0xbb800000, v12
	v_mul_f32_e32 v11, v13, v13
	v_fmac_f32_e32 v11, v12, v12
	v_pk_mul_f32 v[16:17], v[14:15], v[14:15]
	s_nop 0
	v_add_f32_e32 v11, v16, v11
	v_add_f32_e32 v11, v17, v11
	s_nop 1
	v_mov_b32_dpp v16, v11 quad_perm:[1,0,3,2] row_mask:0xf bank_mask:0xf
	s_waitcnt lgkmcnt(0)
	v_add_f32_e32 v11, v11, v16
	s_nop 1
	v_mov_b32_dpp v16, v11 quad_perm:[2,3,0,1] row_mask:0xf bank_mask:0xf
	s_waitcnt lgkmcnt(0)
	v_add_f32_e32 v11, v11, v16
	s_nop 1
	v_mov_b32_dpp v16, v11 row_half_mirror row_mask:0xf bank_mask:0xf
	s_waitcnt lgkmcnt(0)
	v_add_f32_e32 v11, v11, v16
	s_nop 1
	v_mov_b32_dpp v16, v11 row_mirror row_mask:0xf bank_mask:0xf
	s_waitcnt lgkmcnt(0)
	v_add_f32_e32 v11, v11, v16
	v_mov_b32_e32 v16, v11
	s_nop 1
	v_permlane16_swap_b32_e32 v11, v16
	s_waitcnt lgkmcnt(0)
	v_add_f32_e32 v11, v11, v16
	v_mov_b32_e32 v16, v11
	s_nop 1
	v_permlane32_swap_b32_e32 v11, v16
	s_waitcnt lgkmcnt(0)
	v_add_f32_e32 v16, v11, v16
	v_mov_b32_e32 v11, s10
	v_fmamk_f32 v16, v16, 0x3b800000, v11
	v_rsq_f32_e32 v16, v16
	s_nop 0
	v_pk_mul_f32 v[12:13], v[12:13], v[16:17] op_sel_hi:[1,0]
	v_pk_mul_f32 v[14:15], v[14:15], v[16:17] op_sel_hi:[1,0]
	s_waitcnt vmcnt(0)
	v_pk_fma_f32 v[12:13], v[0:1], v[12:13], v[4:5]
	v_pk_fma_f32 v[14:15], v[2:3], v[14:15], v[6:7]
	v_mul_f32_e32 v16, 0xbfb8aa3b, v12
	v_exp_f32_e32 v16, v16
	v_mul_f32_e32 v17, 0xbfb8aa3b, v13
	v_mul_f32_e32 v18, 0xbfb8aa3b, v14
	v_mul_f32_e32 v19, 0xbfb8aa3b, v15
	v_exp_f32_e32 v17, v17
	v_exp_f32_e32 v18, v18
	v_exp_f32_e32 v19, v19
	v_add_f32_e32 v16, 1.0, v16
	v_rcp_f32_e32 v16, v16
	v_add_f32_e32 v17, 1.0, v17
	v_add_f32_e32 v18, 1.0, v18
	v_add_f32_e32 v19, 1.0, v19
	v_rcp_f32_e32 v17, v17
	v_rcp_f32_e32 v18, v18
	v_rcp_f32_e32 v19, v19
	v_mul_f32_e32 v12, v12, v16
	v_mul_f32_e32 v13, v13, v17
	v_mul_f32_e32 v14, v14, v18
	v_mul_f32_e32 v15, v15, v19
	v_cvt_pk_bf16_f32 v16, v12, v13
	v_add_u32_e32 v12, s9, v153
	v_cvt_pk_bf16_f32 v17, v14, v15
	ds_read_b128 v[12:15], v12 offset:49152
	s_waitcnt lgkmcnt(0)
	v_add_f32_e32 v18, v12, v13
	v_add_f32_e32 v18, v14, v18
	v_add_f32_e32 v18, v15, v18
	s_nop 1
	v_mov_b32_dpp v19, v18 quad_perm:[1,0,3,2] row_mask:0xf bank_mask:0xf
	s_waitcnt lgkmcnt(0)
	v_add_f32_e32 v18, v18, v19
	s_nop 1
	v_mov_b32_dpp v19, v18 quad_perm:[2,3,0,1] row_mask:0xf bank_mask:0xf
	s_waitcnt lgkmcnt(0)
	v_add_f32_e32 v18, v18, v19
	s_nop 1
	v_mov_b32_dpp v19, v18 row_half_mirror row_mask:0xf bank_mask:0xf
	s_waitcnt lgkmcnt(0)
	v_add_f32_e32 v18, v18, v19
	s_nop 1
	v_mov_b32_dpp v19, v18 row_mirror row_mask:0xf bank_mask:0xf
	s_waitcnt lgkmcnt(0)
	v_add_f32_e32 v18, v18, v19
	v_mov_b32_e32 v19, v18
	s_nop 1
	v_permlane16_swap_b32_e32 v18, v19
	s_waitcnt lgkmcnt(0)
	v_add_f32_e32 v18, v18, v19
	v_mov_b32_e32 v19, v18
	s_nop 1
	v_permlane32_swap_b32_e32 v18, v19
	s_waitcnt lgkmcnt(0)
	v_add_f32_e32 v18, v18, v19
	v_fmac_f32_e32 v13, 0xbb800000, v18
	v_fmamk_f32 v15, v18, 0xbb800000, v15
	v_fmamk_f32 v14, v18, 0xbb800000, v14
	v_fmamk_f32 v12, v18, 0xbb800000, v12
	v_mul_f32_e32 v20, v13, v13
	v_fmac_f32_e32 v20, v12, v12
	v_pk_mul_f32 v[18:19], v[14:15], v[14:15]
	s_nop 0
	v_add_f32_e32 v18, v18, v20
	v_add_f32_e32 v18, v19, v18
	s_nop 1
	v_mov_b32_dpp v19, v18 quad_perm:[1,0,3,2] row_mask:0xf bank_mask:0xf
	v_lshl_add_u64 v[20:21], v[8:9], 0, s[2:3]
	global_store_dwordx2 v[20:21], v[16:17], off
	s_add_i32 s2, s69, s8
	s_ashr_i32 s3, s2, 31
	s_waitcnt lgkmcnt(0)
	v_add_f32_e32 v18, v18, v19
	s_nop 1
	v_mov_b32_dpp v19, v18 quad_perm:[2,3,0,1] row_mask:0xf bank_mask:0xf
	s_lshl_b64 s[2:3], s[2:3], 9
	s_waitcnt lgkmcnt(0)
	v_add_f32_e32 v18, v18, v19
	s_nop 1
	v_mov_b32_dpp v19, v18 row_half_mirror row_mask:0xf bank_mask:0xf
	s_waitcnt lgkmcnt(0)
	v_add_f32_e32 v18, v18, v19
	s_nop 1
	v_mov_b32_dpp v19, v18 row_mirror row_mask:0xf bank_mask:0xf
	s_waitcnt lgkmcnt(0)
	v_add_f32_e32 v18, v18, v19
	v_mov_b32_e32 v19, v18
	s_nop 1
	v_permlane16_swap_b32_e32 v18, v19
	s_waitcnt lgkmcnt(0)
	v_add_f32_e32 v18, v18, v19
	v_mov_b32_e32 v19, v18
	s_nop 1
	v_permlane32_swap_b32_e32 v18, v19
	s_waitcnt lgkmcnt(0)
	v_add_f32_e32 v18, v18, v19
	v_fmamk_f32 v18, v18, 0x3b800000, v11
	v_rsq_f32_e32 v18, v18
	s_nop 0
	v_pk_mul_f32 v[12:13], v[12:13], v[18:19] op_sel_hi:[1,0]
	v_pk_mul_f32 v[14:15], v[14:15], v[18:19] op_sel_hi:[1,0]
	v_pk_fma_f32 v[12:13], v[0:1], v[12:13], v[4:5]
	v_pk_fma_f32 v[14:15], v[2:3], v[14:15], v[6:7]
	v_mul_f32_e32 v16, 0xbfb8aa3b, v12
	v_exp_f32_e32 v16, v16
	v_mul_f32_e32 v17, 0xbfb8aa3b, v13
	v_mul_f32_e32 v18, 0xbfb8aa3b, v14
	v_mul_f32_e32 v19, 0xbfb8aa3b, v15
	v_exp_f32_e32 v17, v17
	v_exp_f32_e32 v18, v18
	v_exp_f32_e32 v19, v19
	v_add_f32_e32 v16, 1.0, v16
	v_rcp_f32_e32 v16, v16
	v_add_f32_e32 v17, 1.0, v17
	v_add_f32_e32 v18, 1.0, v18
	v_add_f32_e32 v19, 1.0, v19
	v_rcp_f32_e32 v17, v17
	v_rcp_f32_e32 v18, v18
	v_rcp_f32_e32 v19, v19
	v_mul_f32_e32 v12, v12, v16
	v_mul_f32_e32 v13, v13, v17
	v_mul_f32_e32 v14, v14, v18
	v_mul_f32_e32 v15, v15, v19
	v_cvt_pk_bf16_f32 v16, v12, v13
	v_add_u32_e32 v12, s33, v153
	v_cvt_pk_bf16_f32 v17, v14, v15
	ds_read_b128 v[12:15], v12 offset:49152
	s_waitcnt lgkmcnt(0)
	v_add_f32_e32 v18, v12, v13
	v_add_f32_e32 v18, v14, v18
	v_add_f32_e32 v18, v15, v18
	s_nop 1
	v_mov_b32_dpp v19, v18 quad_perm:[1,0,3,2] row_mask:0xf bank_mask:0xf
	s_waitcnt lgkmcnt(0)
	v_add_f32_e32 v18, v18, v19
	s_nop 1
	v_mov_b32_dpp v19, v18 quad_perm:[2,3,0,1] row_mask:0xf bank_mask:0xf
	s_waitcnt lgkmcnt(0)
	v_add_f32_e32 v18, v18, v19
	s_nop 1
	v_mov_b32_dpp v19, v18 row_half_mirror row_mask:0xf bank_mask:0xf
	s_waitcnt lgkmcnt(0)
	v_add_f32_e32 v18, v18, v19
	s_nop 1
	v_mov_b32_dpp v19, v18 row_mirror row_mask:0xf bank_mask:0xf
	s_waitcnt lgkmcnt(0)
	v_add_f32_e32 v18, v18, v19
	v_mov_b32_e32 v19, v18
	s_nop 1
	v_permlane16_swap_b32_e32 v18, v19
	s_waitcnt lgkmcnt(0)
	v_add_f32_e32 v18, v18, v19
	v_mov_b32_e32 v19, v18
	s_nop 1
	v_permlane32_swap_b32_e32 v18, v19
	s_waitcnt lgkmcnt(0)
	v_add_f32_e32 v18, v18, v19
	v_fmac_f32_e32 v13, 0xbb800000, v18
	v_fmamk_f32 v15, v18, 0xbb800000, v15
	v_fmamk_f32 v14, v18, 0xbb800000, v14
	v_fmamk_f32 v12, v18, 0xbb800000, v12
	v_mul_f32_e32 v20, v13, v13
	v_fmac_f32_e32 v20, v12, v12
	v_pk_mul_f32 v[18:19], v[14:15], v[14:15]
	s_nop 0
	v_add_f32_e32 v18, v18, v20
	v_add_f32_e32 v18, v19, v18
	s_nop 1
	v_mov_b32_dpp v19, v18 quad_perm:[1,0,3,2] row_mask:0xf bank_mask:0xf
	v_lshl_add_u64 v[20:21], v[8:9], 0, s[2:3]
	global_store_dwordx2 v[20:21], v[16:17], off
	s_add_i32 s2, s69, s11
	s_ashr_i32 s3, s2, 31
	s_waitcnt lgkmcnt(0)
	v_add_f32_e32 v18, v18, v19
	s_nop 1
	v_mov_b32_dpp v19, v18 quad_perm:[2,3,0,1] row_mask:0xf bank_mask:0xf
	s_lshl_b64 s[2:3], s[2:3], 9
	s_waitcnt lgkmcnt(0)
	v_add_f32_e32 v18, v18, v19
	s_nop 1
	v_mov_b32_dpp v19, v18 row_half_mirror row_mask:0xf bank_mask:0xf
	s_waitcnt lgkmcnt(0)
	v_add_f32_e32 v18, v18, v19
	s_nop 1
	v_mov_b32_dpp v19, v18 row_mirror row_mask:0xf bank_mask:0xf
	s_waitcnt lgkmcnt(0)
	v_add_f32_e32 v18, v18, v19
	v_mov_b32_e32 v19, v18
	s_nop 1
	v_permlane16_swap_b32_e32 v18, v19
	s_waitcnt lgkmcnt(0)
	v_add_f32_e32 v18, v18, v19
	v_mov_b32_e32 v19, v18
	s_nop 1
	v_permlane32_swap_b32_e32 v18, v19
	s_waitcnt lgkmcnt(0)
	v_add_f32_e32 v18, v18, v19
	v_fmamk_f32 v18, v18, 0x3b800000, v11
	v_rsq_f32_e32 v18, v18
	s_nop 0
	v_pk_mul_f32 v[12:13], v[12:13], v[18:19] op_sel_hi:[1,0]
	v_pk_mul_f32 v[14:15], v[14:15], v[18:19] op_sel_hi:[1,0]
	v_pk_fma_f32 v[12:13], v[0:1], v[12:13], v[4:5]
	v_pk_fma_f32 v[14:15], v[2:3], v[14:15], v[6:7]
	v_mul_f32_e32 v16, 0xbfb8aa3b, v12
	v_exp_f32_e32 v16, v16
	v_mul_f32_e32 v17, 0xbfb8aa3b, v13
	v_mul_f32_e32 v18, 0xbfb8aa3b, v14
	v_mul_f32_e32 v19, 0xbfb8aa3b, v15
	v_exp_f32_e32 v17, v17
	v_exp_f32_e32 v18, v18
	v_exp_f32_e32 v19, v19
	v_add_f32_e32 v16, 1.0, v16
	v_rcp_f32_e32 v16, v16
	v_add_f32_e32 v17, 1.0, v17
	v_add_f32_e32 v18, 1.0, v18
	v_add_f32_e32 v19, 1.0, v19
	v_rcp_f32_e32 v17, v17
	v_rcp_f32_e32 v18, v18
	v_rcp_f32_e32 v19, v19
	v_mul_f32_e32 v12, v12, v16
	v_mul_f32_e32 v13, v13, v17
	v_mul_f32_e32 v14, v14, v18
	v_mul_f32_e32 v15, v15, v19
	v_cvt_pk_bf16_f32 v16, v12, v13
	v_add_u32_e32 v12, s58, v153
	v_cvt_pk_bf16_f32 v17, v14, v15
	ds_read_b128 v[12:15], v12 offset:49152
	s_waitcnt lgkmcnt(0)
	v_add_f32_e32 v18, v12, v13
	v_add_f32_e32 v18, v14, v18
	v_add_f32_e32 v18, v15, v18
	s_nop 1
	v_mov_b32_dpp v19, v18 quad_perm:[1,0,3,2] row_mask:0xf bank_mask:0xf
	s_waitcnt lgkmcnt(0)
	v_add_f32_e32 v18, v18, v19
	s_nop 1
	v_mov_b32_dpp v19, v18 quad_perm:[2,3,0,1] row_mask:0xf bank_mask:0xf
	s_waitcnt lgkmcnt(0)
	v_add_f32_e32 v18, v18, v19
	s_nop 1
	v_mov_b32_dpp v19, v18 row_half_mirror row_mask:0xf bank_mask:0xf
	s_waitcnt lgkmcnt(0)
	v_add_f32_e32 v18, v18, v19
	s_nop 1
	v_mov_b32_dpp v19, v18 row_mirror row_mask:0xf bank_mask:0xf
	s_waitcnt lgkmcnt(0)
	v_add_f32_e32 v18, v18, v19
	v_mov_b32_e32 v19, v18
	s_nop 1
	v_permlane16_swap_b32_e32 v18, v19
	s_waitcnt lgkmcnt(0)
	v_add_f32_e32 v18, v18, v19
	v_mov_b32_e32 v19, v18
	s_nop 1
	v_permlane32_swap_b32_e32 v18, v19
	s_waitcnt lgkmcnt(0)
	v_add_f32_e32 v18, v18, v19
	v_fmac_f32_e32 v13, 0xbb800000, v18
	v_fmamk_f32 v15, v18, 0xbb800000, v15
	v_fmamk_f32 v14, v18, 0xbb800000, v14
	v_fmamk_f32 v12, v18, 0xbb800000, v12
	v_mul_f32_e32 v20, v13, v13
	v_fmac_f32_e32 v20, v12, v12
	v_pk_mul_f32 v[18:19], v[14:15], v[14:15]
	s_nop 0
	v_add_f32_e32 v18, v18, v20
	v_add_f32_e32 v18, v19, v18
	s_nop 1
	v_mov_b32_dpp v19, v18 quad_perm:[1,0,3,2] row_mask:0xf bank_mask:0xf
	v_lshl_add_u64 v[20:21], v[8:9], 0, s[2:3]
	global_store_dwordx2 v[20:21], v[16:17], off
	s_add_i32 s2, s69, s35
	s_ashr_i32 s3, s2, 31
	s_waitcnt lgkmcnt(0)
	v_add_f32_e32 v18, v18, v19
	s_nop 1
	v_mov_b32_dpp v19, v18 quad_perm:[2,3,0,1] row_mask:0xf bank_mask:0xf
	s_lshl_b64 s[2:3], s[2:3], 9
	s_waitcnt lgkmcnt(0)
	v_add_f32_e32 v18, v18, v19
	s_nop 1
	v_mov_b32_dpp v19, v18 row_half_mirror row_mask:0xf bank_mask:0xf
	s_waitcnt lgkmcnt(0)
	v_add_f32_e32 v18, v18, v19
	s_nop 1
	v_mov_b32_dpp v19, v18 row_mirror row_mask:0xf bank_mask:0xf
	s_waitcnt lgkmcnt(0)
	v_add_f32_e32 v18, v18, v19
	v_mov_b32_e32 v19, v18
	s_nop 1
	v_permlane16_swap_b32_e32 v18, v19
	s_waitcnt lgkmcnt(0)
	v_add_f32_e32 v18, v18, v19
	v_mov_b32_e32 v19, v18
	s_nop 1
	v_permlane32_swap_b32_e32 v18, v19
	s_waitcnt lgkmcnt(0)
	v_add_f32_e32 v18, v18, v19
	v_fmamk_f32 v18, v18, 0x3b800000, v11
	v_rsq_f32_e32 v18, v18
	s_nop 0
	v_pk_mul_f32 v[12:13], v[12:13], v[18:19] op_sel_hi:[1,0]
	v_pk_mul_f32 v[14:15], v[14:15], v[18:19] op_sel_hi:[1,0]
	v_pk_fma_f32 v[12:13], v[0:1], v[12:13], v[4:5]
	v_pk_fma_f32 v[14:15], v[2:3], v[14:15], v[6:7]
	v_mul_f32_e32 v16, 0xbfb8aa3b, v12
	v_exp_f32_e32 v16, v16
	v_mul_f32_e32 v17, 0xbfb8aa3b, v13
	v_mul_f32_e32 v18, 0xbfb8aa3b, v14
	v_mul_f32_e32 v19, 0xbfb8aa3b, v15
	v_exp_f32_e32 v17, v17
	v_exp_f32_e32 v18, v18
	v_exp_f32_e32 v19, v19
	v_add_f32_e32 v16, 1.0, v16
	v_rcp_f32_e32 v16, v16
	v_add_f32_e32 v17, 1.0, v17
	v_add_f32_e32 v18, 1.0, v18
	v_add_f32_e32 v19, 1.0, v19
	v_rcp_f32_e32 v17, v17
	v_rcp_f32_e32 v18, v18
	v_rcp_f32_e32 v19, v19
	v_mul_f32_e32 v12, v12, v16
	v_mul_f32_e32 v13, v13, v17
	v_mul_f32_e32 v14, v14, v18
	v_mul_f32_e32 v15, v15, v19
	v_cvt_pk_bf16_f32 v16, v12, v13
	v_add_u32_e32 v12, s60, v153
	v_cvt_pk_bf16_f32 v17, v14, v15
	ds_read_b128 v[12:15], v12 offset:49152
	s_waitcnt lgkmcnt(0)
	v_add_f32_e32 v18, v12, v13
	v_add_f32_e32 v18, v14, v18
	v_add_f32_e32 v18, v15, v18
	s_nop 1
	v_mov_b32_dpp v19, v18 quad_perm:[1,0,3,2] row_mask:0xf bank_mask:0xf
	s_waitcnt lgkmcnt(0)
	v_add_f32_e32 v18, v18, v19
	s_nop 1
	v_mov_b32_dpp v19, v18 quad_perm:[2,3,0,1] row_mask:0xf bank_mask:0xf
	s_waitcnt lgkmcnt(0)
	v_add_f32_e32 v18, v18, v19
	s_nop 1
	v_mov_b32_dpp v19, v18 row_half_mirror row_mask:0xf bank_mask:0xf
	s_waitcnt lgkmcnt(0)
	v_add_f32_e32 v18, v18, v19
	s_nop 1
	v_mov_b32_dpp v19, v18 row_mirror row_mask:0xf bank_mask:0xf
	s_waitcnt lgkmcnt(0)
	v_add_f32_e32 v18, v18, v19
	v_mov_b32_e32 v19, v18
	s_nop 1
	v_permlane16_swap_b32_e32 v18, v19
	s_waitcnt lgkmcnt(0)
	v_add_f32_e32 v18, v18, v19
	v_mov_b32_e32 v19, v18
	s_nop 1
	v_permlane32_swap_b32_e32 v18, v19
	s_waitcnt lgkmcnt(0)
	v_add_f32_e32 v18, v18, v19
	v_fmac_f32_e32 v13, 0xbb800000, v18
	v_fmamk_f32 v15, v18, 0xbb800000, v15
	v_fmamk_f32 v14, v18, 0xbb800000, v14
	v_fmamk_f32 v12, v18, 0xbb800000, v12
	v_mul_f32_e32 v20, v13, v13
	v_fmac_f32_e32 v20, v12, v12
	v_pk_mul_f32 v[18:19], v[14:15], v[14:15]
	s_nop 0
	v_add_f32_e32 v18, v18, v20
	v_add_f32_e32 v18, v19, v18
	s_nop 1
	v_mov_b32_dpp v19, v18 quad_perm:[1,0,3,2] row_mask:0xf bank_mask:0xf
	v_lshl_add_u64 v[20:21], v[8:9], 0, s[2:3]
	global_store_dwordx2 v[20:21], v[16:17], off
	s_add_i32 s2, s69, s59
	s_ashr_i32 s3, s2, 31
	s_waitcnt lgkmcnt(0)
	v_add_f32_e32 v18, v18, v19
	s_nop 1
	v_mov_b32_dpp v19, v18 quad_perm:[2,3,0,1] row_mask:0xf bank_mask:0xf
	s_lshl_b64 s[2:3], s[2:3], 9
	s_waitcnt lgkmcnt(0)
	v_add_f32_e32 v18, v18, v19
	s_nop 1
	v_mov_b32_dpp v19, v18 row_half_mirror row_mask:0xf bank_mask:0xf
	s_waitcnt lgkmcnt(0)
	v_add_f32_e32 v18, v18, v19
	s_nop 1
	v_mov_b32_dpp v19, v18 row_mirror row_mask:0xf bank_mask:0xf
	s_waitcnt lgkmcnt(0)
	v_add_f32_e32 v18, v18, v19
	v_mov_b32_e32 v19, v18
	s_nop 1
	v_permlane16_swap_b32_e32 v18, v19
	s_waitcnt lgkmcnt(0)
	v_add_f32_e32 v18, v18, v19
	v_mov_b32_e32 v19, v18
	s_nop 1
	v_permlane32_swap_b32_e32 v18, v19
	s_waitcnt lgkmcnt(0)
	v_add_f32_e32 v18, v18, v19
	v_fmamk_f32 v18, v18, 0x3b800000, v11
	v_rsq_f32_e32 v18, v18
	s_nop 0
	v_pk_mul_f32 v[12:13], v[12:13], v[18:19] op_sel_hi:[1,0]
	v_pk_mul_f32 v[14:15], v[14:15], v[18:19] op_sel_hi:[1,0]
	v_pk_fma_f32 v[12:13], v[0:1], v[12:13], v[4:5]
	v_pk_fma_f32 v[14:15], v[2:3], v[14:15], v[6:7]
	v_mul_f32_e32 v16, 0xbfb8aa3b, v12
	v_exp_f32_e32 v16, v16
	v_mul_f32_e32 v17, 0xbfb8aa3b, v13
	v_mul_f32_e32 v18, 0xbfb8aa3b, v14
	v_mul_f32_e32 v19, 0xbfb8aa3b, v15
	v_exp_f32_e32 v17, v17
	v_exp_f32_e32 v18, v18
	v_exp_f32_e32 v19, v19
	v_add_f32_e32 v16, 1.0, v16
	v_rcp_f32_e32 v16, v16
	v_add_f32_e32 v17, 1.0, v17
	v_add_f32_e32 v18, 1.0, v18
	v_add_f32_e32 v19, 1.0, v19
	v_rcp_f32_e32 v17, v17
	v_rcp_f32_e32 v18, v18
	v_rcp_f32_e32 v19, v19
	v_mul_f32_e32 v12, v12, v16
	v_mul_f32_e32 v13, v13, v17
	v_mul_f32_e32 v14, v14, v18
	v_mul_f32_e32 v15, v15, v19
	v_cvt_pk_bf16_f32 v16, v12, v13
	v_add_u32_e32 v12, s62, v153
	v_cvt_pk_bf16_f32 v17, v14, v15
	ds_read_b128 v[12:15], v12 offset:49152
	s_waitcnt lgkmcnt(0)
	v_add_f32_e32 v18, v12, v13
	v_add_f32_e32 v18, v14, v18
	v_add_f32_e32 v18, v15, v18
	s_nop 1
	v_mov_b32_dpp v19, v18 quad_perm:[1,0,3,2] row_mask:0xf bank_mask:0xf
	s_waitcnt lgkmcnt(0)
	v_add_f32_e32 v18, v18, v19
	s_nop 1
	v_mov_b32_dpp v19, v18 quad_perm:[2,3,0,1] row_mask:0xf bank_mask:0xf
	s_waitcnt lgkmcnt(0)
	v_add_f32_e32 v18, v18, v19
	s_nop 1
	v_mov_b32_dpp v19, v18 row_half_mirror row_mask:0xf bank_mask:0xf
	s_waitcnt lgkmcnt(0)
	v_add_f32_e32 v18, v18, v19
	s_nop 1
	v_mov_b32_dpp v19, v18 row_mirror row_mask:0xf bank_mask:0xf
	s_waitcnt lgkmcnt(0)
	v_add_f32_e32 v18, v18, v19
	v_mov_b32_e32 v19, v18
	s_nop 1
	v_permlane16_swap_b32_e32 v18, v19
	s_waitcnt lgkmcnt(0)
	v_add_f32_e32 v18, v18, v19
	v_mov_b32_e32 v19, v18
	s_nop 1
	v_permlane32_swap_b32_e32 v18, v19
	s_waitcnt lgkmcnt(0)
	v_add_f32_e32 v18, v18, v19
	v_fmac_f32_e32 v13, 0xbb800000, v18
	v_fmamk_f32 v15, v18, 0xbb800000, v15
	v_fmamk_f32 v14, v18, 0xbb800000, v14
	v_fmamk_f32 v12, v18, 0xbb800000, v12
	v_mul_f32_e32 v20, v13, v13
	v_fmac_f32_e32 v20, v12, v12
	v_pk_mul_f32 v[18:19], v[14:15], v[14:15]
	s_nop 0
	v_add_f32_e32 v18, v18, v20
	v_add_f32_e32 v18, v19, v18
	s_nop 1
	v_mov_b32_dpp v19, v18 quad_perm:[1,0,3,2] row_mask:0xf bank_mask:0xf
	v_lshl_add_u64 v[20:21], v[8:9], 0, s[2:3]
	global_store_dwordx2 v[20:21], v[16:17], off
	s_add_i32 s2, s69, s61
	s_ashr_i32 s3, s2, 31
	s_waitcnt lgkmcnt(0)
	v_add_f32_e32 v18, v18, v19
	s_nop 1
	v_mov_b32_dpp v19, v18 quad_perm:[2,3,0,1] row_mask:0xf bank_mask:0xf
	s_lshl_b64 s[2:3], s[2:3], 9
	s_waitcnt lgkmcnt(0)
	v_add_f32_e32 v18, v18, v19
	s_nop 1
	v_mov_b32_dpp v19, v18 row_half_mirror row_mask:0xf bank_mask:0xf
	s_waitcnt lgkmcnt(0)
	v_add_f32_e32 v18, v18, v19
	s_nop 1
	v_mov_b32_dpp v19, v18 row_mirror row_mask:0xf bank_mask:0xf
	s_waitcnt lgkmcnt(0)
	v_add_f32_e32 v18, v18, v19
	v_mov_b32_e32 v19, v18
	s_nop 1
	v_permlane16_swap_b32_e32 v18, v19
	s_waitcnt lgkmcnt(0)
	v_add_f32_e32 v18, v18, v19
	v_mov_b32_e32 v19, v18
	s_nop 1
	v_permlane32_swap_b32_e32 v18, v19
	s_waitcnt lgkmcnt(0)
	v_add_f32_e32 v18, v18, v19
	v_fmamk_f32 v18, v18, 0x3b800000, v11
	v_rsq_f32_e32 v18, v18
	s_nop 0
	v_pk_mul_f32 v[12:13], v[12:13], v[18:19] op_sel_hi:[1,0]
	v_pk_mul_f32 v[14:15], v[14:15], v[18:19] op_sel_hi:[1,0]
	v_pk_fma_f32 v[12:13], v[0:1], v[12:13], v[4:5]
	v_pk_fma_f32 v[14:15], v[2:3], v[14:15], v[6:7]
	v_mul_f32_e32 v16, 0xbfb8aa3b, v12
	v_exp_f32_e32 v16, v16
	v_mul_f32_e32 v17, 0xbfb8aa3b, v13
	v_mul_f32_e32 v18, 0xbfb8aa3b, v14
	v_mul_f32_e32 v19, 0xbfb8aa3b, v15
	v_exp_f32_e32 v17, v17
	v_exp_f32_e32 v18, v18
	v_exp_f32_e32 v19, v19
	v_add_f32_e32 v16, 1.0, v16
	v_rcp_f32_e32 v16, v16
	v_add_f32_e32 v17, 1.0, v17
	v_add_f32_e32 v18, 1.0, v18
	v_add_f32_e32 v19, 1.0, v19
	v_rcp_f32_e32 v17, v17
	v_rcp_f32_e32 v18, v18
	v_rcp_f32_e32 v19, v19
	v_mul_f32_e32 v12, v12, v16
	v_mul_f32_e32 v13, v13, v17
	v_mul_f32_e32 v14, v14, v18
	v_mul_f32_e32 v15, v15, v19
	v_cvt_pk_bf16_f32 v16, v12, v13
	v_add_u32_e32 v12, s64, v153
	v_cvt_pk_bf16_f32 v17, v14, v15
	ds_read_b128 v[12:15], v12 offset:49152
	s_waitcnt lgkmcnt(0)
	v_add_f32_e32 v18, v12, v13
	v_add_f32_e32 v18, v14, v18
	v_add_f32_e32 v18, v15, v18
	s_nop 1
	v_mov_b32_dpp v19, v18 quad_perm:[1,0,3,2] row_mask:0xf bank_mask:0xf
	s_waitcnt lgkmcnt(0)
	v_add_f32_e32 v18, v18, v19
	s_nop 1
	v_mov_b32_dpp v19, v18 quad_perm:[2,3,0,1] row_mask:0xf bank_mask:0xf
	s_waitcnt lgkmcnt(0)
	v_add_f32_e32 v18, v18, v19
	s_nop 1
	v_mov_b32_dpp v19, v18 row_half_mirror row_mask:0xf bank_mask:0xf
	s_waitcnt lgkmcnt(0)
	v_add_f32_e32 v18, v18, v19
	s_nop 1
	v_mov_b32_dpp v19, v18 row_mirror row_mask:0xf bank_mask:0xf
	s_waitcnt lgkmcnt(0)
	v_add_f32_e32 v18, v18, v19
	v_mov_b32_e32 v19, v18
	s_nop 1
	v_permlane16_swap_b32_e32 v18, v19
	s_waitcnt lgkmcnt(0)
	v_add_f32_e32 v18, v18, v19
	v_mov_b32_e32 v19, v18
	s_nop 1
	v_permlane32_swap_b32_e32 v18, v19
	s_waitcnt lgkmcnt(0)
	v_add_f32_e32 v18, v18, v19
	v_fmac_f32_e32 v13, 0xbb800000, v18
	v_fmamk_f32 v15, v18, 0xbb800000, v15
	v_fmamk_f32 v14, v18, 0xbb800000, v14
	v_fmamk_f32 v12, v18, 0xbb800000, v12
	v_mul_f32_e32 v20, v13, v13
	v_fmac_f32_e32 v20, v12, v12
	v_pk_mul_f32 v[18:19], v[14:15], v[14:15]
	s_nop 0
	v_add_f32_e32 v18, v18, v20
	v_add_f32_e32 v18, v19, v18
	s_nop 1
	v_mov_b32_dpp v19, v18 quad_perm:[1,0,3,2] row_mask:0xf bank_mask:0xf
	v_lshl_add_u64 v[20:21], v[8:9], 0, s[2:3]
	global_store_dwordx2 v[20:21], v[16:17], off
	s_add_i32 s2, s69, s63
	s_ashr_i32 s3, s2, 31
	s_waitcnt lgkmcnt(0)
	v_add_f32_e32 v18, v18, v19
	s_nop 1
	v_mov_b32_dpp v19, v18 quad_perm:[2,3,0,1] row_mask:0xf bank_mask:0xf
	s_lshl_b64 s[2:3], s[2:3], 9
	s_waitcnt lgkmcnt(0)
	v_add_f32_e32 v18, v18, v19
	s_nop 1
	v_mov_b32_dpp v19, v18 row_half_mirror row_mask:0xf bank_mask:0xf
	s_waitcnt lgkmcnt(0)
	v_add_f32_e32 v18, v18, v19
	s_nop 1
	v_mov_b32_dpp v19, v18 row_mirror row_mask:0xf bank_mask:0xf
	s_waitcnt lgkmcnt(0)
	v_add_f32_e32 v18, v18, v19
	v_mov_b32_e32 v19, v18
	s_nop 1
	v_permlane16_swap_b32_e32 v18, v19
	s_waitcnt lgkmcnt(0)
	v_add_f32_e32 v18, v18, v19
	v_mov_b32_e32 v19, v18
	s_nop 1
	v_permlane32_swap_b32_e32 v18, v19
	s_waitcnt lgkmcnt(0)
	v_add_f32_e32 v18, v18, v19
	v_fmamk_f32 v18, v18, 0x3b800000, v11
	v_rsq_f32_e32 v18, v18
	s_nop 0
	v_pk_mul_f32 v[12:13], v[12:13], v[18:19] op_sel_hi:[1,0]
	v_pk_mul_f32 v[14:15], v[14:15], v[18:19] op_sel_hi:[1,0]
	v_pk_fma_f32 v[12:13], v[0:1], v[12:13], v[4:5]
	v_pk_fma_f32 v[14:15], v[2:3], v[14:15], v[6:7]
	v_mul_f32_e32 v16, 0xbfb8aa3b, v12
	v_exp_f32_e32 v16, v16
	v_mul_f32_e32 v17, 0xbfb8aa3b, v13
	v_mul_f32_e32 v18, 0xbfb8aa3b, v14
	v_mul_f32_e32 v19, 0xbfb8aa3b, v15
	v_exp_f32_e32 v17, v17
	v_exp_f32_e32 v18, v18
	v_exp_f32_e32 v19, v19
	v_add_f32_e32 v16, 1.0, v16
	v_rcp_f32_e32 v16, v16
	v_add_f32_e32 v17, 1.0, v17
	v_add_f32_e32 v18, 1.0, v18
	v_add_f32_e32 v19, 1.0, v19
	v_rcp_f32_e32 v17, v17
	v_rcp_f32_e32 v18, v18
	v_rcp_f32_e32 v19, v19
	v_mul_f32_e32 v12, v12, v16
	v_mul_f32_e32 v13, v13, v17
	v_mul_f32_e32 v14, v14, v18
	v_mul_f32_e32 v15, v15, v19
	v_cvt_pk_bf16_f32 v16, v12, v13
	v_add_u32_e32 v12, s67, v153
	v_cvt_pk_bf16_f32 v17, v14, v15
	ds_read_b128 v[12:15], v12 offset:49152
	s_waitcnt lgkmcnt(0)
	v_add_f32_e32 v18, v12, v13
	v_add_f32_e32 v18, v14, v18
	v_add_f32_e32 v18, v15, v18
	s_nop 1
	v_mov_b32_dpp v19, v18 quad_perm:[1,0,3,2] row_mask:0xf bank_mask:0xf
	s_waitcnt lgkmcnt(0)
	v_add_f32_e32 v18, v18, v19
	s_nop 1
	v_mov_b32_dpp v19, v18 quad_perm:[2,3,0,1] row_mask:0xf bank_mask:0xf
	s_waitcnt lgkmcnt(0)
	v_add_f32_e32 v18, v18, v19
	s_nop 1
	v_mov_b32_dpp v19, v18 row_half_mirror row_mask:0xf bank_mask:0xf
	s_waitcnt lgkmcnt(0)
	v_add_f32_e32 v18, v18, v19
	s_nop 1
	v_mov_b32_dpp v19, v18 row_mirror row_mask:0xf bank_mask:0xf
	s_waitcnt lgkmcnt(0)
	v_add_f32_e32 v18, v18, v19
	v_mov_b32_e32 v19, v18
	s_nop 1
	v_permlane16_swap_b32_e32 v18, v19
	s_waitcnt lgkmcnt(0)
	v_add_f32_e32 v18, v18, v19
	v_mov_b32_e32 v19, v18
	s_nop 1
	v_permlane32_swap_b32_e32 v18, v19
	s_waitcnt lgkmcnt(0)
	v_add_f32_e32 v18, v18, v19
	v_fmac_f32_e32 v13, 0xbb800000, v18
	v_fmamk_f32 v15, v18, 0xbb800000, v15
	v_fmamk_f32 v14, v18, 0xbb800000, v14
	v_fmamk_f32 v12, v18, 0xbb800000, v12
	v_mul_f32_e32 v20, v13, v13
	v_fmac_f32_e32 v20, v12, v12
	v_pk_mul_f32 v[18:19], v[14:15], v[14:15]
	s_nop 0
	v_add_f32_e32 v18, v18, v20
	v_add_f32_e32 v18, v19, v18
	s_nop 1
	v_mov_b32_dpp v19, v18 quad_perm:[1,0,3,2] row_mask:0xf bank_mask:0xf
	v_lshl_add_u64 v[20:21], v[8:9], 0, s[2:3]
	s_add_i32 s2, s69, s66
	s_ashr_i32 s3, s2, 31
	s_lshl_b64 s[2:3], s[2:3], 9
	s_waitcnt lgkmcnt(0)
	v_add_f32_e32 v18, v18, v19
	s_nop 1
	v_mov_b32_dpp v19, v18 quad_perm:[2,3,0,1] row_mask:0xf bank_mask:0xf
	global_store_dwordx2 v[20:21], v[16:17], off
	s_cmpk_gt_i32 s68, 0xff
	s_waitcnt lgkmcnt(0)
	v_add_f32_e32 v18, v18, v19
	s_nop 1
	v_mov_b32_dpp v19, v18 row_half_mirror row_mask:0xf bank_mask:0xf
	s_waitcnt lgkmcnt(0)
	v_add_f32_e32 v18, v18, v19
	s_nop 1
	v_mov_b32_dpp v19, v18 row_mirror row_mask:0xf bank_mask:0xf
	s_waitcnt lgkmcnt(0)
	v_add_f32_e32 v18, v18, v19
	v_mov_b32_e32 v19, v18
	s_nop 1
	v_permlane16_swap_b32_e32 v18, v19
	s_waitcnt lgkmcnt(0)
	v_add_f32_e32 v18, v18, v19
	v_mov_b32_e32 v19, v18
	s_nop 1
	v_permlane32_swap_b32_e32 v18, v19
	s_waitcnt lgkmcnt(0)
	v_add_f32_e32 v18, v18, v19
	v_fmac_f32_e32 v11, 0x3b800000, v18
	v_rsq_f32_e32 v18, v11
	s_nop 0
	v_pk_mul_f32 v[12:13], v[12:13], v[18:19] op_sel_hi:[1,0]
	v_pk_mul_f32 v[14:15], v[14:15], v[18:19] op_sel_hi:[1,0]
	v_pk_fma_f32 v[0:1], v[0:1], v[12:13], v[4:5]
	v_pk_fma_f32 v[2:3], v[2:3], v[14:15], v[6:7]
	v_mul_f32_e32 v4, 0xbfb8aa3b, v0
	v_mul_f32_e32 v5, 0xbfb8aa3b, v1
	v_mul_f32_e32 v6, 0xbfb8aa3b, v2
	v_mul_f32_e32 v7, 0xbfb8aa3b, v3
	v_exp_f32_e32 v4, v4
	v_exp_f32_e32 v5, v5
	v_exp_f32_e32 v6, v6
	v_exp_f32_e32 v7, v7
	v_add_f32_e32 v4, 1.0, v4
	v_add_f32_e32 v5, 1.0, v5
	v_add_f32_e32 v6, 1.0, v6
	v_add_f32_e32 v7, 1.0, v7
	v_rcp_f32_e32 v4, v4
	v_rcp_f32_e32 v5, v5
	v_rcp_f32_e32 v6, v6
	v_rcp_f32_e32 v7, v7
	v_mul_f32_e32 v0, v0, v4
	v_mul_f32_e32 v1, v1, v5
	v_mul_f32_e32 v2, v2, v6
	v_mul_f32_e32 v3, v3, v7
	v_cvt_pk_bf16_f32 v0, v0, v1
	v_cvt_pk_bf16_f32 v1, v2, v3
	v_lshl_add_u64 v[2:3], v[8:9], 0, s[2:3]
	global_store_dwordx2 v[2:3], v[0:1], off
	s_barrier
	s_cbranch_scc1 .LBB0_298

.LBB0_409:
	global_load_dwordx4 v[28:31], v[16:17], off
	s_waitcnt vmcnt(4)
	v_mul_f32_e32 v27, v13, v13
	s_waitcnt vmcnt(3)
	v_mul_f32_e32 v42, v9, v9
	s_waitcnt vmcnt(1)
	v_pk_mul_f32 v[36:37], v[0:1], v[0:1]
	v_pk_mul_f32 v[38:39], v[4:5], v[4:5]
	v_pk_mul_f32 v[32:33], v[2:3], v[2:3]
	v_pk_mul_f32 v[34:35], v[6:7], v[6:7]
	v_fmac_f32_e32 v27, v12, v12
	v_fmac_f32_e32 v42, v8, v8
	v_mov_b32_e32 v40, v36
	v_mov_b32_e32 v41, v38
	v_mov_b32_e32 v38, v37
	v_mov_b32_e32 v36, v32
	v_mov_b32_e32 v37, v34
	v_mov_b32_e32 v34, v33
	v_fmac_f32_e32 v27, v14, v14
	v_fmac_f32_e32 v42, v10, v10
	v_pk_add_f32 v[32:33], v[40:41], v[38:39]
	v_fmac_f32_e32 v27, v15, v15
	v_fmac_f32_e32 v42, v11, v11
	v_pk_add_f32 v[32:33], v[36:37], v[32:33]
	v_add_f32_e32 v27, v27, v42
	v_pk_add_f32 v[32:33], v[34:35], v[32:33]
	s_mov_b32 s2, 0xe5f00000
	v_add_f32_e32 v27, v33, v27
	v_add_f32_e32 v27, v32, v27
	s_nop 1
	v_mov_b32_dpp v32, v27 quad_perm:[1,0,3,2] row_mask:0xf bank_mask:0xf
	v_mov_b32_e32 v33, s0
	v_add_co_u32_e32 v34, vcc, s2, v18
	s_mov_b32 s2, 0xe5f01000
	s_waitcnt lgkmcnt(0)
	v_add_f32_e32 v27, v27, v32
	s_nop 1
	v_mov_b32_dpp v32, v27 quad_perm:[2,3,0,1] row_mask:0xf bank_mask:0xf
	v_addc_co_u32_e32 v35, vcc, -1, v19, vcc
	s_add_i32 s38, s38, s42
	s_add_u32 s54, s54, s56
	s_waitcnt lgkmcnt(0)
	v_add_f32_e32 v27, v27, v32
	s_nop 1
	v_mov_b32_dpp v32, v27 row_half_mirror row_mask:0xf bank_mask:0xf
	s_addc_u32 s55, s55, s57
	s_add_u32 s58, s58, s56
	s_addc_u32 s59, s59, s57
	s_cmp_ge_i32 s38, s1
	s_waitcnt lgkmcnt(0)
	v_add_f32_e32 v27, v27, v32
	s_nop 1
	v_mov_b32_dpp v32, v27 row_mirror row_mask:0xf bank_mask:0xf
	s_waitcnt lgkmcnt(0)
	v_add_f32_e32 v27, v27, v32
	v_mov_b32_e32 v32, v27
	s_nop 1
	v_permlane16_swap_b32_e32 v27, v32
	s_waitcnt lgkmcnt(0)
	v_add_f32_e32 v27, v27, v32
	v_mov_b32_e32 v32, v27
	s_nop 1
	v_permlane32_swap_b32_e32 v27, v32
	s_waitcnt lgkmcnt(0)
	v_add_f32_e32 v27, v27, v32
	v_fmamk_f32 v27, v27, 0x3a800000, v33
	v_rsq_f32_e32 v32, v27
	s_nop 0
	v_pk_mul_f32 v[12:13], v[12:13], v[32:33] op_sel_hi:[1,0]
	v_pk_mul_f32 v[14:15], v[14:15], v[32:33] op_sel_hi:[1,0]
	v_pk_mul_f32 v[8:9], v[8:9], v[32:33] op_sel_hi:[1,0]
	v_pk_mul_f32 v[10:11], v[10:11], v[32:33] op_sel_hi:[1,0]
	v_pk_mul_f32 v[4:5], v[4:5], v[32:33] op_sel_hi:[1,0]
	v_pk_mul_f32 v[6:7], v[6:7], v[32:33] op_sel_hi:[1,0]
	v_pk_mul_f32 v[0:1], v[0:1], v[32:33] op_sel_hi:[1,0]
	v_pk_mul_f32 v[2:3], v[2:3], v[32:33] op_sel_hi:[1,0]
	s_waitcnt vmcnt(0)
	v_pk_mul_f32 v[12:13], v[28:29], v[12:13]
	v_pk_mul_f32 v[14:15], v[30:31], v[14:15]
	v_cvt_pk_bf16_f32 v12, v12, v13
	v_add_co_u32_e32 v28, vcc, s2, v18
	v_cvt_pk_bf16_f32 v13, v14, v15
	global_store_dwordx2 v[34:35], v[12:13], off
	global_load_dwordx4 v[12:15], v[16:17], off offset:1024
	v_addc_co_u32_e32 v29, vcc, -1, v19, vcc
	v_lshl_add_u64 v[18:19], v[18:19], 0, s[52:53]
	s_waitcnt vmcnt(0)
	v_pk_mul_f32 v[8:9], v[12:13], v[8:9]
	v_pk_mul_f32 v[10:11], v[14:15], v[10:11]
	v_cvt_pk_bf16_f32 v8, v8, v9
	s_nop 0
	v_cvt_pk_bf16_f32 v9, v10, v11
	global_store_dwordx2 v[28:29], v[8:9], off offset:-3584
	global_load_dwordx4 v[8:11], v[16:17], off offset:2048
	s_waitcnt vmcnt(0)
	v_pk_mul_f32 v[4:5], v[8:9], v[4:5]
	v_pk_mul_f32 v[6:7], v[10:11], v[6:7]
	v_cvt_pk_bf16_f32 v4, v4, v5
	s_nop 0
	v_cvt_pk_bf16_f32 v5, v6, v7
	global_store_dwordx2 v[28:29], v[4:5], off offset:-3072
	global_load_dwordx4 v[4:7], v[16:17], off offset:3072
	s_waitcnt vmcnt(0)
	v_pk_mul_f32 v[0:1], v[0:1], v[4:5]
	v_pk_mul_f32 v[2:3], v[2:3], v[6:7]
	v_cvt_pk_bf16_f32 v0, v0, v1
	s_nop 0
	v_cvt_pk_bf16_f32 v1, v2, v3
	global_store_dwordx2 v[28:29], v[0:1], off offset:-2560
	s_cbranch_scc1 .LBB0_412
.LBB0_410:
	v_lshl_add_u64 v[0:1], s[54:55], 0, v[168:169]
	global_load_dwordx4 v[12:15], v[0:1], off
	global_load_dwordx4 v[8:11], v[0:1], off offset:1024
	global_load_dwordx4 v[4:7], v[0:1], off offset:2048
	s_nop 0
	global_load_dwordx4 v[0:3], v[0:1], off offset:3072
	s_andn2_b64 vcc, exec, s[44:45]
	s_cbranch_vccnz .LBB0_409
	global_load_dwordx2 v[32:33], v[18:19], off
	global_load_dwordx2 v[34:35], v[18:19], off offset:512
	global_load_dwordx2 v[36:37], v[18:19], off offset:1536
	global_load_dwordx2 v[38:39], v[18:19], off offset:1024
	s_load_dwordx2 s[2:3], s[40:41], 0x18
	s_waitcnt lgkmcnt(0)
	s_add_u32 s2, s2, s46
	s_addc_u32 s3, s3, s47
	global_load_dwordx4 v[28:31], v26, s[2:3]
	s_waitcnt vmcnt(4)
	v_and_b32_e32 v41, 0xffff0000, v32
	s_waitcnt vmcnt(3)
	v_and_b32_e32 v43, 0xffff0000, v34
	v_lshlrev_b32_e32 v40, 16, v32
	v_lshlrev_b32_e32 v42, 16, v34
	s_waitcnt vmcnt(2)
	v_and_b32_e32 v47, 0xffff0000, v36
	s_waitcnt vmcnt(1)
	v_and_b32_e32 v46, 0xffff0000, v38
	v_mul_f32_e32 v27, v41, v41
	v_mul_f32_e32 v50, v43, v43
	v_lshlrev_b32_e32 v32, 16, v33
	v_lshlrev_b32_e32 v34, 16, v35
	v_lshlrev_b32_e32 v45, 16, v36
	v_lshlrev_b32_e32 v44, 16, v38
	v_lshlrev_b32_e32 v48, 16, v39
	v_and_b32_e32 v36, 0xffff0000, v39
	v_pk_mul_f32 v[38:39], v[46:47], v[46:47]
	v_fmac_f32_e32 v27, v40, v40
	v_fmac_f32_e32 v50, v42, v42
	v_and_b32_e32 v33, 0xffff0000, v33
	v_and_b32_e32 v35, 0xffff0000, v35
	v_lshlrev_b32_e32 v49, 16, v37
	v_pk_fma_f32 v[38:39], v[44:45], v[44:45], v[38:39]
	v_fmac_f32_e32 v27, v32, v32
	v_fmac_f32_e32 v50, v34, v34
	v_and_b32_e32 v37, 0xffff0000, v37
	v_pk_fma_f32 v[38:39], v[48:49], v[48:49], v[38:39]
	v_fmac_f32_e32 v27, v33, v33
	v_fmac_f32_e32 v50, v35, v35
	v_pk_fma_f32 v[38:39], v[36:37], v[36:37], v[38:39]
	v_add_f32_e32 v27, v27, v50
	v_add_f32_e32 v27, v27, v38
	v_add_f32_e32 v27, v27, v39
	s_nop 1
	v_mov_b32_dpp v38, v27 quad_perm:[1,0,3,2] row_mask:0xf bank_mask:0xf
	v_mov_b32_e32 v39, s0
	v_lshl_add_u64 v[50:51], s[58:59], 0, v[168:169]
	s_waitcnt lgkmcnt(0)
	v_add_f32_e32 v27, v27, v38
	s_nop 1
	v_mov_b32_dpp v38, v27 quad_perm:[2,3,0,1] row_mask:0xf bank_mask:0xf
	s_waitcnt lgkmcnt(0)
	v_add_f32_e32 v27, v27, v38
	s_nop 1
	v_mov_b32_dpp v38, v27 row_half_mirror row_mask:0xf bank_mask:0xf
	s_waitcnt lgkmcnt(0)
	v_add_f32_e32 v27, v27, v38
	s_nop 1
	v_mov_b32_dpp v38, v27 row_mirror row_mask:0xf bank_mask:0xf
	s_waitcnt lgkmcnt(0)
	v_add_f32_e32 v27, v27, v38
	v_mov_b32_e32 v38, v27
	s_nop 1
	v_permlane16_swap_b32_e32 v27, v38
	s_waitcnt lgkmcnt(0)
	v_add_f32_e32 v27, v27, v38
	v_mov_b32_e32 v38, v27
	s_nop 1
	v_permlane32_swap_b32_e32 v27, v38
	s_waitcnt lgkmcnt(0)
	v_add_f32_e32 v27, v27, v38
	v_fmamk_f32 v27, v27, 0x3a800000, v39
	v_rsq_f32_e32 v38, v27
	s_nop 0
	v_pk_mul_f32 v[40:41], v[40:41], v[38:39] op_sel_hi:[1,0]
	v_pk_mul_f32 v[32:33], v[32:33], v[38:39] op_sel_hi:[1,0]
	s_waitcnt vmcnt(0)
	v_pk_fma_f32 v[12:13], v[28:29], v[40:41], v[12:13]
	v_pk_fma_f32 v[14:15], v[30:31], v[32:33], v[14:15]
	global_store_dwordx4 v[50:51], v[12:15], off
	global_load_dwordx4 v[28:31], v26, s[2:3] offset:1024
	v_pk_mul_f32 v[32:33], v[42:43], v[38:39] op_sel_hi:[1,0]
	v_pk_mul_f32 v[34:35], v[34:35], v[38:39] op_sel_hi:[1,0]
	s_waitcnt vmcnt(0)
	v_pk_fma_f32 v[8:9], v[28:29], v[32:33], v[8:9]
	v_pk_fma_f32 v[10:11], v[30:31], v[34:35], v[10:11]
	global_store_dwordx4 v[50:51], v[8:11], off offset:1024
	global_load_dwordx4 v[28:31], v26, s[2:3] offset:2048
	v_mov_b32_e32 v32, v44
	v_mov_b32_e32 v33, v46
	v_mov_b32_e32 v34, v48
	v_mov_b32_e32 v35, v36
	v_pk_mul_f32 v[32:33], v[32:33], v[38:39] op_sel_hi:[1,0]
	v_pk_mul_f32 v[34:35], v[34:35], v[38:39] op_sel_hi:[1,0]
	v_mov_b32_e32 v46, v45
	v_mov_b32_e32 v36, v49
	s_waitcnt vmcnt(0)
	v_pk_fma_f32 v[6:7], v[30:31], v[34:35], v[6:7]
	v_pk_fma_f32 v[4:5], v[28:29], v[32:33], v[4:5]
	global_store_dwordx4 v[50:51], v[4:7], off offset:2048
	global_load_dwordx4 v[28:31], v26, s[2:3] offset:3072
	v_pk_mul_f32 v[32:33], v[46:47], v[38:39] op_sel_hi:[1,0]
	v_pk_mul_f32 v[34:35], v[36:37], v[38:39] op_sel_hi:[1,0]
	s_waitcnt vmcnt(0)
	v_pk_fma_f32 v[0:1], v[28:29], v[32:33], v[0:1]
	v_pk_fma_f32 v[2:3], v[30:31], v[34:35], v[2:3]
	global_store_dwordx4 v[50:51], v[0:3], off offset:3072
	s_branch .LBB0_409
